# st_pair permlane + MLA V-read hoist, placeholder nops dropped; wait states re-derived by a hazard pass cross-checked against every compiler pad in the baseline
# baseline (speedup 1.0000x reference)
.LBB0_415:
	s_or_b64 exec, exec, s[0:1]
	s_waitcnt vmcnt(0)
	v_add_f32_e32 v32, 0, v32
	v_add_f32_e32 v32, v32, v33
	v_add_f32_e32 v32, v32, v34
	v_add_f32_e32 v32, v32, v35
	v_add_f32_e32 v32, v32, v36
	v_add_f32_e32 v32, v32, v37
	v_fmamk_f32 v32, v32, 0x3b2aaaab, v252
	v_mul_f32_e32 v33, 0x4b800000, v32
	v_cmp_gt_f32_e64 s[0:1], s25, v32
	s_nop 1
	v_cndmask_b32_e64 v32, v32, v33, s[0:1]
	v_rsq_f32_e32 v34, v32
	v_mov_b64_e32 v[32:33], s[22:23]
	v_mul_f32_e32 v35, 0x45800000, v34
	v_cndmask_b32_e64 v34, v34, v35, s[0:1]
	v_mul_f32_e32 v34, 0x3dd53b94, v34
	v_pk_mul_f32 v[26:27], v[34:35], v[26:27] op_sel_hi:[0,1]
	v_pk_mul_f32 v[24:25], v[34:35], v[24:25] op_sel_hi:[0,1]
	v_pk_mul_f32 v[30:31], v[34:35], v[30:31] op_sel_hi:[0,1]
	v_pk_mul_f32 v[28:29], v[34:35], v[28:29] op_sel_hi:[0,1]
	s_nop 0
	v_cndmask_b32_e32 v35, v24, v28, vcc
	ds_bpermute_b32 v35, v130, v35
	v_mad_i64_i32 v[32:33], s[0:1], v40, s8, v[32:33]
	v_lshl_add_u64 v[32:33], v[32:33], 0, v[128:129]
	s_waitcnt lgkmcnt(0)
	v_cndmask_b32_e32 v24, v35, v24, vcc
	v_cndmask_b32_e32 v28, v28, v35, vcc
	s_waitcnt lgkmcnt(0)
	s_nop 1
	v_permlane16_swap_b32_e32 v25, v29
	s_waitcnt lgkmcnt(0)
	s_waitcnt lgkmcnt(0)
	s_nop 1
	v_permlane16_swap_b32_e32 v26, v30
	s_nop 1
	v_permlane16_swap_b32_e32 v27, v31
	v_cvt_pk_bf16_f32 v24, v24, v25
	v_cvt_pk_bf16_f32 v25, v26, v27
	v_cvt_pk_bf16_f32 v26, v28, v29
	v_lshl_add_u64 v[28:29], v[32:33], 0, v[104:105]
	v_cvt_pk_bf16_f32 v27, v30, v31
	v_lshl_add_u64 v[28:29], v[28:29], 0, v[176:177]
	v_pk_mul_f32 v[22:23], v[34:35], v[22:23] op_sel_hi:[0,1]
	v_pk_mul_f32 v[20:21], v[34:35], v[20:21] op_sel_hi:[0,1]
	v_pk_mul_f32 v[18:19], v[34:35], v[18:19] op_sel_hi:[0,1]
	v_pk_mul_f32 v[16:17], v[34:35], v[16:17] op_sel_hi:[0,1]
	global_store_dwordx4 v[28:29], v[24:27], off
	v_cndmask_b32_e32 v29, v23, v19, vcc
	ds_bpermute_b32 v29, v130, v29
	v_mov_b64_e32 v[24:25], s[34:35]
	v_mad_i64_i32 v[24:25], s[0:1], v40, s8, v[24:25]
	v_lshl_add_u64 v[24:25], v[24:25], 0, v[128:129]
	s_waitcnt lgkmcnt(1)
	v_mov_b32_e32 v26, v16
	s_nop 1
	v_permlane16_swap_b32_e32 v20, v26
	s_waitcnt lgkmcnt(1)
	v_mov_b32_e32 v16, v21
	v_mov_b32_e32 v21, v17
	s_nop 1
	v_permlane16_swap_b32_e32 v16, v21
	s_waitcnt lgkmcnt(1)
	v_mov_b32_e32 v17, v22
	v_mov_b32_e32 v22, v18
	s_nop 1
	v_permlane16_swap_b32_e32 v17, v22
	s_waitcnt lgkmcnt(0)
	v_cndmask_b32_e32 v18, v29, v23, vcc
	v_cvt_pk_bf16_f32 v16, v20, v16
	v_cvt_pk_bf16_f32 v17, v17, v18
	v_cvt_pk_bf16_f32 v18, v26, v21
	v_lshl_add_u64 v[20:21], v[24:25], 0, v[104:105]
	v_cndmask_b32_e32 v19, v19, v29, vcc
	v_lshl_add_u64 v[20:21], v[20:21], 0, v[176:177]
	s_mov_b32 s0, 0x3900000
	v_cvt_pk_bf16_f32 v19, v22, v19
	v_add_co_u32_e64 v20, s[0:1], s0, v20
	v_or_b32_e32 v22, 0x70, v143
	s_nop 0
	v_addc_co_u32_e64 v21, s[0:1], 0, v21, s[0:1]
	v_or_b32_e32 v24, v144, v22
	global_store_dwordx4 v[20:21], v[16:19], off offset:64
	s_nop 1
	v_lshlrev_b32_e32 v16, 3, v24
	v_ashrrev_i32_e32 v17, 31, v16
	v_lshl_add_u64 v[16:17], v[16:17], 2, s[4:5]
	global_load_dwordx2 v[20:21], v[16:17], off offset:16
	s_nop 0
	global_load_dwordx4 v[16:19], v[16:17], off
	s_and_saveexec_b64 s[0:1], s[40:41]
	s_cbranch_execz .LBB0_417
	v_or_b32_e32 v22, v142, v22
	v_lshlrev_b32_e32 v22, 7, v22
	v_mov_b32_e32 v23, v177
	v_lshl_add_u64 v[34:35], v[134:135], 0, v[22:23]
	v_lshl_add_u64 v[36:37], v[132:133], 0, v[22:23]
	global_load_dwordx4 v[26:29], v[34:35], off
	global_load_dwordx4 v[30:33], v[36:37], off
	s_waitcnt vmcnt(0)
	v_pk_mul_f32 v[38:39], v[8:9], v[30:31]
	v_pk_mul_f32 v[22:23], v[0:1], v[30:31]
	v_mul_f32_e32 v30, v10, v28
	v_mul_f32_e32 v40, v2, v32
	v_mul_f32_e32 v42, v10, v32
	v_mul_f32_e32 v28, v2, v28
	v_mov_b32_e32 v2, v11
	v_mov_b32_e32 v32, v29
	v_mov_b32_e32 v10, v3
	v_pk_mul_f32 v[44:45], v[2:3], v[32:33]
	v_pk_mul_f32 v[2:3], v[10:11], v[32:33]
	v_mov_b32_e32 v31, v44
	v_mov_b32_e32 v41, v45
	v_mov_b32_e32 v29, v2
	v_mov_b32_e32 v43, v3
	v_pk_fma_f32 v[8:9], v[8:9], v[26:27], v[22:23] neg_lo:[0,0,1] neg_hi:[0,0,1]
	v_pk_add_f32 v[22:23], v[30:31], v[40:41] neg_lo:[0,1] neg_hi:[0,1]
	v_pk_fma_f32 v[0:1], v[0:1], v[26:27], v[38:39]
	v_pk_add_f32 v[2:3], v[28:29], v[42:43]
	global_load_dwordx4 v[26:29], v[34:35], off offset:64
	global_load_dwordx4 v[30:33], v[36:37], off offset:64
	s_waitcnt vmcnt(1)
	v_mul_f32_e32 v34, v14, v28
	s_waitcnt vmcnt(0)
	v_mul_f32_e32 v36, v6, v32
	v_mul_f32_e32 v38, v14, v32
	v_mul_f32_e32 v28, v6, v28
	v_mov_b32_e32 v6, v15
	v_mov_b32_e32 v32, v29
	v_pk_mul_f32 v[40:41], v[6:7], v[32:33]
	v_mov_b32_e32 v14, v7
	v_pk_mul_f32 v[10:11], v[12:13], v[30:31]
	v_pk_mul_f32 v[30:31], v[4:5], v[30:31]
	v_mov_b32_e32 v35, v40
	v_mov_b32_e32 v37, v41
	v_pk_mul_f32 v[6:7], v[14:15], v[32:33]
	v_pk_fma_f32 v[12:13], v[12:13], v[26:27], v[30:31] neg_lo:[0,0,1] neg_hi:[0,0,1]
	v_pk_add_f32 v[30:31], v[34:35], v[36:37] neg_lo:[0,1] neg_hi:[0,1]
	v_mov_b32_e32 v29, v6
	v_mov_b32_e32 v39, v7
	v_pk_fma_f32 v[4:5], v[4:5], v[26:27], v[10:11]
	v_pk_add_f32 v[6:7], v[28:29], v[38:39]
	v_mov_b32_e32 v14, v30
	v_mov_b32_e32 v15, v31
	v_mov_b32_e32 v10, v22
	v_mov_b32_e32 v11, v23
.LBB0_417:
	s_or_b64 exec, exec, s[0:1]
	s_waitcnt vmcnt(0)
	v_add_f32_e32 v16, 0, v16
	v_add_f32_e32 v16, v16, v17
	v_add_f32_e32 v16, v16, v18
	v_add_f32_e32 v16, v16, v19
	v_add_f32_e32 v16, v16, v20
	v_add_f32_e32 v16, v16, v21
	v_fmamk_f32 v16, v16, 0x3b2aaaab, v252
	v_mul_f32_e32 v17, 0x4b800000, v16
	v_cmp_gt_f32_e64 s[0:1], s25, v16
	v_mov_b32_e32 v105, v177
	s_nop 0
	v_cndmask_b32_e64 v16, v16, v17, s[0:1]
	v_rsq_f32_e32 v18, v16
	v_mov_b64_e32 v[16:17], s[22:23]
	v_mul_f32_e32 v19, 0x45800000, v18
	v_cndmask_b32_e64 v18, v18, v19, s[0:1]
	v_mul_f32_e32 v18, 0x3dd53b94, v18
	v_pk_mul_f32 v[10:11], v[18:19], v[10:11] op_sel_hi:[0,1]
	v_pk_mul_f32 v[8:9], v[18:19], v[8:9] op_sel_hi:[0,1]
	v_pk_mul_f32 v[14:15], v[18:19], v[14:15] op_sel_hi:[0,1]
	v_pk_mul_f32 v[12:13], v[18:19], v[12:13] op_sel_hi:[0,1]
	s_nop 0
	v_cndmask_b32_e32 v19, v8, v12, vcc
	ds_bpermute_b32 v19, v130, v19
	v_mad_i64_i32 v[16:17], s[0:1], v24, s8, v[16:17]
	v_lshl_add_u64 v[16:17], v[16:17], 0, v[128:129]
	s_waitcnt lgkmcnt(0)
	v_cndmask_b32_e32 v8, v19, v8, vcc
	v_cndmask_b32_e32 v12, v12, v19, vcc
	s_waitcnt lgkmcnt(0)
	s_nop 1
	v_permlane16_swap_b32_e32 v9, v13
	s_waitcnt lgkmcnt(0)
	s_waitcnt lgkmcnt(0)
	s_nop 1
	v_permlane16_swap_b32_e32 v10, v14
	s_nop 1
	v_permlane16_swap_b32_e32 v11, v15
	v_cvt_pk_bf16_f32 v8, v8, v9
	v_cvt_pk_bf16_f32 v9, v10, v11
	v_cvt_pk_bf16_f32 v10, v12, v13
	v_lshl_add_u64 v[12:13], v[16:17], 0, v[104:105]
	v_cvt_pk_bf16_f32 v11, v14, v15
	v_lshl_add_u64 v[12:13], v[12:13], 0, v[176:177]
	v_pk_mul_f32 v[2:3], v[18:19], v[2:3] op_sel_hi:[0,1]
	v_pk_mul_f32 v[0:1], v[18:19], v[0:1] op_sel_hi:[0,1]
	v_pk_mul_f32 v[6:7], v[18:19], v[6:7] op_sel_hi:[0,1]
	v_pk_mul_f32 v[4:5], v[18:19], v[4:5] op_sel_hi:[0,1]
	global_store_dwordx4 v[12:13], v[8:11], off
	v_cndmask_b32_e32 v12, v2, v6, vcc
	v_cndmask_b32_e32 v13, v3, v7, vcc
	ds_bpermute_b32 v12, v130, v12
	ds_bpermute_b32 v13, v130, v13
	v_mov_b64_e32 v[8:9], s[34:35]
	v_mad_i64_i32 v[8:9], s[0:1], v24, s8, v[8:9]
	v_lshl_add_u64 v[8:9], v[8:9], 0, v[128:129]
	s_waitcnt lgkmcnt(2)
	s_nop 1
	v_permlane16_swap_b32_e32 v0, v4
	s_waitcnt lgkmcnt(2)
	s_nop 1
	v_permlane16_swap_b32_e32 v1, v5
	s_waitcnt lgkmcnt(1)
	v_cndmask_b32_e32 v2, v12, v2, vcc
	s_waitcnt lgkmcnt(0)
	v_cndmask_b32_e32 v3, v13, v3, vcc
	v_cvt_pk_bf16_f32 v0, v0, v1
	v_cvt_pk_bf16_f32 v1, v2, v3
	v_cvt_pk_bf16_f32 v2, v4, v5
	v_lshl_add_u64 v[4:5], v[8:9], 0, v[104:105]
	v_lshl_add_u64 v[4:5], v[4:5], 0, v[176:177]
	v_cndmask_b32_e32 v6, v6, v12, vcc
	v_cndmask_b32_e32 v7, v7, v13, vcc
	v_add_co_u32_e32 v4, vcc, 0x3900000, v4
	v_cvt_pk_bf16_f32 v3, v6, v7
	s_nop 0
	v_addc_co_u32_e32 v5, vcc, 0, v5, vcc
	global_store_dwordx4 v[4:5], v[0:3], off offset:64

.LBB0_479:
	v_add_u32_e32 v0, 0xfffff000, v104
	v_ashrrev_i32_e32 v0, 10, v0
	v_add_u32_e32 v0, 1, v0
	v_cmp_lt_i32_e32 vcc, s81, v97
	v_ashrrev_i32_e32 v105, 31, v104
	v_lshlrev_b64 v[112:113], 11, v[104:105]
	v_cndmask_b32_e32 v4, 0, v0, vcc
	v_lshlrev_b64 v[0:1], 12, v[104:105]
	v_lshl_add_u64 v[72:73], v[102:103], 0, v[0:1]
	v_lshl_add_u64 v[0:1], v[98:99], 0, v[112:113]
	global_load_dwordx2 v[2:3], v[0:1], off
	global_load_dwordx2 v[8:9], v[0:1], off offset:512
	global_load_dwordx2 v[10:11], v[0:1], off offset:1024
	global_load_dwordx2 v[32:33], v[0:1], off offset:1536
	v_add_u32_e32 v34, 1, v104
	v_ashrrev_i32_e32 v35, 31, v34
	v_lshlrev_b64 v[110:111], 11, v[34:35]
	v_lshl_add_u64 v[0:1], v[98:99], 0, v[110:111]
	global_load_dwordx2 v[48:49], v[0:1], off
	global_load_dwordx2 v[52:53], v[0:1], off offset:512
	global_load_dwordx2 v[46:47], v[0:1], off offset:1024
	global_load_dwordx2 v[44:45], v[0:1], off offset:1536
	v_add_u32_e32 v80, 2, v104
	v_ashrrev_i32_e32 v81, 31, v80
	v_add_u32_e32 v74, 3, v104
	v_lshlrev_b64 v[108:109], 11, v[80:81]
	v_ashrrev_i32_e32 v75, 31, v74
	v_lshl_add_u64 v[0:1], v[98:99], 0, v[108:109]
	v_lshlrev_b64 v[106:107], 11, v[74:75]
	s_mul_i32 s0, s12, 5
	global_load_dwordx2 v[62:63], v[0:1], off
	global_load_dwordx2 v[60:61], v[0:1], off offset:512
	global_load_dwordx2 v[78:79], v[0:1], off offset:1024
	global_load_dwordx2 v[76:77], v[0:1], off offset:1536
	v_lshl_add_u64 v[0:1], v[98:99], 0, v[106:107]
	v_add_u32_e32 v105, s0, v4
	global_load_dwordx2 v[70:71], v[0:1], off
	global_load_dwordx2 v[68:69], v[0:1], off offset:512
	global_load_dwordx2 v[66:67], v[0:1], off offset:1024
	global_load_dwordx2 v[64:65], v[0:1], off offset:1536
	v_mul_hi_i32_i24_e32 v1, 0x3000, v105
	v_mul_i32_i24_e32 v0, 0x3000, v105
	v_lshl_add_u64 v[0:1], s[4:5], 0, v[0:1]
	v_lshlrev_b32_e32 v176, 2, v96
	v_lshl_add_u64 v[0:1], v[0:1], 0, v[176:177]
	s_mov_b64 s[0:1], 0x2000
	v_lshl_add_u64 v[50:51], v[0:1], 0, s[0:1]
	s_movk_i32 s1, 0x2000
	v_add_co_u32_e32 v0, vcc, s1, v0
	global_load_dwordx4 v[16:19], v[72:73], off
	s_nop 0
	v_addc_co_u32_e32 v1, vcc, 0, v1, vcc
	global_load_dwordx4 v[4:7], v[0:1], off
	s_movk_i32 s0, 0x1000
	s_mov_b32 s10, 0x3a800000
	s_waitcnt vmcnt(17)
	v_and_b32_e32 v41, 0xffff0000, v2
	s_waitcnt vmcnt(16)
	v_and_b32_e32 v43, 0xffff0000, v8
	v_lshlrev_b32_e32 v40, 16, v2
	v_lshlrev_b32_e32 v42, 16, v8
	v_mov_b32_e32 v24, v41
	v_mov_b32_e32 v25, v43
	v_lshlrev_b32_e32 v36, 16, v3
	v_lshlrev_b32_e32 v38, 16, v9
	v_mov_b32_e32 v14, v40
	v_mov_b32_e32 v15, v42
	v_pk_mul_f32 v[24:25], v[24:25], v[24:25]
	v_and_b32_e32 v37, 0xffff0000, v3
	global_load_dwordx4 v[20:23], v[72:73], off offset:1024
	global_load_dwordx4 v[0:3], v[50:51], off offset:1024
	v_and_b32_e32 v39, 0xffff0000, v9
	v_mov_b32_e32 v8, v36
	v_mov_b32_e32 v9, v38
	v_pk_fma_f32 v[14:15], v[14:15], v[14:15], v[24:25]
	v_mov_b32_e32 v12, v37
	v_mov_b32_e32 v13, v39
	v_pk_fma_f32 v[8:9], v[8:9], v[8:9], v[14:15]
	s_waitcnt vmcnt(17)
	v_lshlrev_b32_e32 v82, 16, v11
	v_pk_fma_f32 v[88:89], v[12:13], v[12:13], v[8:9]
	global_load_dwordx4 v[24:27], v[72:73], off offset:2048
	global_load_dwordx4 v[12:15], v[50:51], off offset:2048
	v_and_b32_e32 v83, 0xffff0000, v11
	v_lshlrev_b32_e32 v86, 16, v10
	v_and_b32_e32 v87, 0xffff0000, v10
	global_load_dwordx4 v[28:31], v[72:73], off offset:3072
	global_load_dwordx4 v[8:11], v[50:51], off offset:3072
	s_waitcnt vmcnt(20)
	v_and_b32_e32 v91, 0xffff0000, v32
	v_lshlrev_b32_e32 v90, 16, v32
	v_mov_b32_e32 v56, v87
	v_mov_b32_e32 v57, v91
	v_mov_b32_e32 v54, v86
	v_mov_b32_e32 v55, v90
	v_pk_mul_f32 v[56:57], v[56:57], v[56:57]
	v_lshlrev_b32_e32 v84, 16, v33
	v_pk_fma_f32 v[54:55], v[54:55], v[54:55], v[56:57]
	v_add_co_u32_e32 v56, vcc, s0, v72
	v_and_b32_e32 v85, 0xffff0000, v33
	s_nop 0
	v_addc_co_u32_e32 v57, vcc, 0, v73, vcc
	v_mov_b32_e32 v32, v82
	v_mov_b32_e32 v33, v84
	v_add_co_u32_e32 v92, vcc, s1, v72
	v_mov_b32_e32 v50, v83
	v_mov_b32_e32 v51, v85
	v_pk_fma_f32 v[32:33], v[32:33], v[32:33], v[54:55]
	v_addc_co_u32_e32 v93, vcc, 0, v73, vcc
	s_waitcnt vmcnt(19)
	v_and_b32_e32 v123, 0xffff0000, v48
	s_waitcnt vmcnt(18)
	v_and_b32_e32 v121, 0xffff0000, v52
	v_pk_fma_f32 v[94:95], v[50:51], v[50:51], v[32:33]
	v_lshlrev_b64 v[50:51], 12, v[34:35]
	global_load_dwordx4 v[32:35], v[92:93], off offset:-4096
	v_lshlrev_b32_e32 v122, 16, v48
	v_lshlrev_b32_e32 v120, 16, v52
	v_mov_b32_e32 v124, v123
	v_mov_b32_e32 v125, v121
	v_lshlrev_b32_e32 v116, 16, v49
	v_lshlrev_b32_e32 v118, 16, v53
	v_mov_b32_e32 v58, v122
	v_mov_b32_e32 v59, v120
	v_pk_mul_f32 v[124:125], v[124:125], v[124:125]
	v_and_b32_e32 v117, 0xffff0000, v49
	v_lshl_add_u64 v[114:115], v[102:103], 0, v[50:51]
	global_load_dwordx4 v[48:51], v[56:57], off offset:1024
	v_and_b32_e32 v119, 0xffff0000, v53
	v_mov_b32_e32 v52, v116
	v_mov_b32_e32 v53, v118
	v_pk_fma_f32 v[58:59], v[58:59], v[58:59], v[124:125]
	v_mov_b32_e32 v54, v117
	v_mov_b32_e32 v55, v119
	v_pk_fma_f32 v[52:53], v[52:53], v[52:53], v[58:59]
	s_waitcnt vmcnt(19)
	v_and_b32_e32 v129, 0xffff0000, v46
	v_pk_fma_f32 v[132:133], v[54:55], v[54:55], v[52:53]
	global_load_dwordx4 v[52:55], v[56:57], off offset:2048
	s_waitcnt vmcnt(19)
	v_and_b32_e32 v131, 0xffff0000, v44
	global_load_dwordx4 v[56:59], v[56:57], off offset:3072
	v_lshlrev_b32_e32 v128, 16, v46
	v_lshlrev_b32_e32 v130, 16, v44
	v_mov_b32_e32 v136, v129
	v_mov_b32_e32 v137, v131
	v_lshlrev_b32_e32 v124, 16, v47
	v_lshlrev_b32_e32 v126, 16, v45
	v_mov_b32_e32 v134, v128
	v_mov_b32_e32 v135, v130
	v_pk_mul_f32 v[136:137], v[136:137], v[136:137]
	v_and_b32_e32 v125, 0xffff0000, v47
	v_and_b32_e32 v127, 0xffff0000, v45
	v_mov_b32_e32 v44, v124
	v_mov_b32_e32 v45, v126
	v_pk_fma_f32 v[134:135], v[134:135], v[134:135], v[136:137]
	v_mov_b32_e32 v46, v125
	v_mov_b32_e32 v47, v127
	v_pk_fma_f32 v[44:45], v[44:45], v[44:45], v[134:135]
	s_mov_b32 s0, 0x358637bd
	v_pk_fma_f32 v[44:45], v[46:47], v[46:47], v[44:45]
	v_mov_b32_e32 v46, v132
	v_mov_b32_e32 v47, v88
	v_mov_b32_e32 v88, v133
	v_pk_add_f32 v[46:47], v[46:47], v[88:89]
	v_mov_b32_e32 v88, v44
	v_mov_b32_e32 v89, v94
	v_pk_add_f32 v[46:47], v[46:47], v[88:89]
	v_mov_b32_e32 v94, v45
	v_pk_add_f32 v[44:45], v[46:47], v[94:95]
	ds_bpermute_b32 v47, v148, v45
	ds_bpermute_b32 v46, v148, v44
	v_mov_b64_e32 v[88:89], s[0:1]
	s_waitcnt vmcnt(15)
	v_and_b32_e32 v135, 0xffff0000, v70
	s_waitcnt vmcnt(14)
	v_and_b32_e32 v139, 0xffff0000, v68
	v_lshlrev_b32_e32 v134, 16, v70
	s_waitcnt lgkmcnt(0)
	v_pk_add_f32 v[44:45], v[44:45], v[46:47]
	ds_bpermute_b32 v47, v149, v45
	ds_bpermute_b32 v46, v149, v44
	v_lshlrev_b32_e32 v138, 16, v68
	v_lshlrev_b32_e32 v136, 16, v69
	v_and_b32_e32 v137, 0xffff0000, v69
	v_mov_b32_e32 v69, v136
	s_waitcnt lgkmcnt(0)
	v_pk_add_f32 v[44:45], v[44:45], v[46:47]
	ds_bpermute_b32 v47, v150, v45
	ds_bpermute_b32 v46, v150, v44
	s_waitcnt vmcnt(13)
	v_and_b32_e32 v145, 0xffff0000, v66
	s_waitcnt vmcnt(12)
	v_and_b32_e32 v147, 0xffff0000, v64
	v_lshlrev_b32_e32 v144, 16, v66
	v_lshlrev_b32_e32 v146, 16, v64
	s_waitcnt lgkmcnt(0)
	v_pk_add_f32 v[44:45], v[44:45], v[46:47]
	ds_bpermute_b32 v47, v151, v45
	ds_bpermute_b32 v46, v151, v44
	v_mov_b32_e32 v154, v145
	v_mov_b32_e32 v155, v147
	v_lshlrev_b32_e32 v140, 16, v67
	v_lshlrev_b32_e32 v142, 16, v65
	s_waitcnt lgkmcnt(0)
	v_pk_add_f32 v[44:45], v[44:45], v[46:47]
	ds_bpermute_b32 v47, v152, v45
	ds_bpermute_b32 v46, v152, v44
	v_pk_mul_f32 v[154:155], v[154:155], v[154:155]
	v_and_b32_e32 v141, 0xffff0000, v67
	v_and_b32_e32 v143, 0xffff0000, v65
	v_mov_b32_e32 v64, v140
	s_waitcnt lgkmcnt(0)
	v_pk_add_f32 v[44:45], v[44:45], v[46:47]
	ds_bpermute_b32 v47, v153, v45
	ds_bpermute_b32 v46, v153, v44
	v_mov_b32_e32 v65, v142
	v_mov_b32_e32 v66, v141
	v_mov_b32_e32 v67, v143
	s_waitcnt lgkmcnt(0)
	v_pk_add_f32 v[44:45], v[44:45], v[46:47]
	s_nop 0
	v_pk_fma_f32 v[94:95], v[44:45], s[10:11], v[88:89] op_sel_hi:[1,0,0]
	s_nop 0
	v_mul_f32_e32 v44, 0x4b800000, v95
	v_cmp_gt_f32_e64 s[0:1], s25, v95
	v_cmp_gt_f32_e32 vcc, s25, v94
	s_nop 0
	v_cndmask_b32_e64 v44, v95, v44, s[0:1]
	v_rsq_f32_e32 v44, v44
	v_and_b32_e32 v95, 0xffff0000, v63
	v_mul_f32_e32 v45, 0x45800000, v44
	v_cndmask_b32_e64 v132, v44, v45, s[0:1]
	v_pk_mul_f32 v[40:41], v[132:133], v[40:41] op_sel_hi:[0,1]
	s_waitcnt vmcnt(10)
	v_pk_fma_f32 v[44:45], v[4:5], v[40:41], v[16:17]
	v_pk_mul_f32 v[16:17], v[132:133], v[36:37] op_sel_hi:[0,1]
	s_nop 0
	v_pk_fma_f32 v[46:47], v[6:7], v[16:17], v[18:19]
	v_pk_mul_f32 v[16:17], v[132:133], v[42:43] op_sel_hi:[0,1]
	s_waitcnt vmcnt(8)
	v_pk_fma_f32 v[40:41], v[0:1], v[16:17], v[20:21]
	v_pk_mul_f32 v[16:17], v[132:133], v[38:39] op_sel_hi:[0,1]
	s_nop 0
	v_pk_fma_f32 v[42:43], v[2:3], v[16:17], v[22:23]
	v_pk_mul_f32 v[16:17], v[132:133], v[86:87] op_sel_hi:[0,1]
	s_waitcnt vmcnt(6)
	v_pk_fma_f32 v[36:37], v[12:13], v[16:17], v[24:25]
	v_pk_mul_f32 v[16:17], v[132:133], v[82:83] op_sel_hi:[0,1]
	s_nop 0
	v_pk_fma_f32 v[38:39], v[14:15], v[16:17], v[26:27]
	v_pk_mul_f32 v[16:17], v[132:133], v[90:91] op_sel_hi:[0,1]
	s_waitcnt vmcnt(4)
	v_pk_fma_f32 v[28:29], v[8:9], v[16:17], v[28:29]
	v_pk_mul_f32 v[16:17], v[132:133], v[84:85] op_sel_hi:[0,1]
	s_nop 0
	v_pk_fma_f32 v[30:31], v[10:11], v[16:17], v[30:31]
	v_mul_f32_e32 v16, 0x4b800000, v94
	v_cndmask_b32_e32 v16, v94, v16, vcc
	v_rsq_f32_e32 v16, v16
	v_lshlrev_b32_e32 v94, 16, v63
	global_store_dwordx4 v[72:73], v[44:47], off
	global_store_dwordx4 v[72:73], v[40:43], off offset:1024
	v_mul_f32_e32 v17, 0x45800000, v16
	v_cndmask_b32_e32 v18, v16, v17, vcc
	v_pk_mul_f32 v[16:17], v[18:19], v[122:123] op_sel_hi:[0,1]
	s_waitcnt vmcnt(5)
	v_pk_fma_f32 v[20:21], v[4:5], v[16:17], v[32:33]
	v_pk_mul_f32 v[16:17], v[18:19], v[116:117] op_sel_hi:[0,1]
	s_nop 0
	v_pk_fma_f32 v[22:23], v[6:7], v[16:17], v[34:35]
	v_pk_mul_f32 v[16:17], v[18:19], v[120:121] op_sel_hi:[0,1]
	s_waitcnt vmcnt(4)
	v_pk_fma_f32 v[32:33], v[0:1], v[16:17], v[48:49]
	v_pk_mul_f32 v[16:17], v[18:19], v[118:119] op_sel_hi:[0,1]
	s_nop 0
	v_pk_fma_f32 v[34:35], v[2:3], v[16:17], v[50:51]
	v_pk_mul_f32 v[16:17], v[18:19], v[128:129] op_sel_hi:[0,1]
	s_waitcnt vmcnt(3)
	v_pk_fma_f32 v[24:25], v[12:13], v[16:17], v[52:53]
	v_pk_mul_f32 v[16:17], v[18:19], v[124:125] op_sel_hi:[0,1]
	s_nop 0
	v_pk_fma_f32 v[26:27], v[14:15], v[16:17], v[54:55]
	v_pk_mul_f32 v[16:17], v[18:19], v[130:131] op_sel_hi:[0,1]
	v_pk_mul_f32 v[18:19], v[18:19], v[126:127] op_sel_hi:[0,1]
	global_store_dwordx4 v[114:115], v[20:23], off
	s_waitcnt vmcnt(3)
	v_pk_fma_f32 v[16:17], v[8:9], v[16:17], v[56:57]
	v_pk_fma_f32 v[18:19], v[10:11], v[18:19], v[58:59]
	global_store_dwordx4 v[114:115], v[32:35], off offset:1024
	global_store_dwordx4 v[114:115], v[24:27], off offset:2048
	global_store_dwordx4 v[114:115], v[16:19], off offset:3072
	global_load_dwordx4 v[48:51], v[92:93], off
	v_and_b32_e32 v115, 0xffff0000, v62
	v_and_b32_e32 v119, 0xffff0000, v60
	v_lshlrev_b64 v[52:53], 12, v[80:81]
	v_lshlrev_b32_e32 v114, 16, v62
	v_lshlrev_b32_e32 v118, 16, v60
	v_mov_b32_e32 v62, v115
	v_mov_b32_e32 v63, v119
	v_lshl_add_u64 v[90:91], v[102:103], 0, v[52:53]
	global_load_dwordx4 v[52:55], v[92:93], off offset:1024
	v_lshlrev_b32_e32 v116, 16, v61
	v_and_b32_e32 v117, 0xffff0000, v61
	v_mov_b32_e32 v60, v114
	v_mov_b32_e32 v61, v118
	v_pk_mul_f32 v[62:63], v[62:63], v[62:63]
	v_mov_b32_e32 v56, v94
	v_mov_b32_e32 v57, v116
	v_pk_fma_f32 v[60:61], v[60:61], v[60:61], v[62:63]
	v_mov_b32_e32 v58, v95
	v_pk_fma_f32 v[56:57], v[56:57], v[56:57], v[60:61]
	global_load_dwordx4 v[60:63], v[92:93], off offset:2048
	v_mov_b32_e32 v59, v117
	v_pk_fma_f32 v[126:127], v[58:59], v[58:59], v[56:57]
	global_load_dwordx4 v[56:59], v[92:93], off offset:3072
	v_and_b32_e32 v125, 0xffff0000, v78
	v_and_b32_e32 v121, 0xffff0000, v76
	v_lshlrev_b32_e32 v124, 16, v78
	v_lshlrev_b32_e32 v120, 16, v76
	v_mov_b32_e32 v82, v125
	v_mov_b32_e32 v83, v121
	v_lshlrev_b32_e32 v122, 16, v79
	v_lshlrev_b32_e32 v92, 16, v77
	v_mov_b32_e32 v80, v124
	v_mov_b32_e32 v81, v120
	v_pk_mul_f32 v[82:83], v[82:83], v[82:83]
	v_and_b32_e32 v123, 0xffff0000, v79
	v_and_b32_e32 v93, 0xffff0000, v77
	v_mov_b32_e32 v76, v122
	v_mov_b32_e32 v77, v92
	v_pk_fma_f32 v[80:81], v[80:81], v[80:81], v[82:83]
	v_add_co_u32_e32 v84, vcc, s29, v72
	v_mov_b32_e32 v78, v123
	v_mov_b32_e32 v79, v93
	v_pk_fma_f32 v[76:77], v[76:77], v[76:77], v[80:81]
	v_addc_co_u32_e32 v85, vcc, 0, v73, vcc
	global_store_dwordx4 v[72:73], v[36:39], off offset:2048
	global_store_dwordx4 v[72:73], v[28:31], off offset:3072
	v_pk_fma_f32 v[128:129], v[78:79], v[78:79], v[76:77]
	v_lshlrev_b64 v[76:77], 12, v[74:75]
	global_load_dwordx4 v[72:75], v[84:85], off
	v_mov_b32_e32 v82, v135
	v_mov_b32_e32 v83, v139
	v_lshlrev_b32_e32 v132, 16, v71
	v_lshl_add_u64 v[130:131], v[102:103], 0, v[76:77]
	global_load_dwordx4 v[76:79], v[84:85], off offset:1024
	v_mov_b32_e32 v80, v134
	v_mov_b32_e32 v81, v138
	v_pk_mul_f32 v[82:83], v[82:83], v[82:83]
	v_mov_b32_e32 v68, v132
	v_pk_fma_f32 v[80:81], v[80:81], v[80:81], v[82:83]
	v_and_b32_e32 v133, 0xffff0000, v71
	v_pk_fma_f32 v[68:69], v[68:69], v[68:69], v[80:81]
	global_load_dwordx4 v[80:83], v[84:85], off offset:2048
	v_mov_b32_e32 v70, v133
	global_load_dwordx4 v[84:87], v[84:85], off offset:3072
	v_mov_b32_e32 v71, v137
	v_pk_fma_f32 v[68:69], v[70:71], v[70:71], v[68:69]
	v_mov_b32_e32 v70, v144
	v_mov_b32_e32 v71, v146
	v_pk_fma_f32 v[70:71], v[70:71], v[70:71], v[154:155]
	s_nop 0
	v_pk_fma_f32 v[64:65], v[64:65], v[64:65], v[70:71]
	s_nop 0
	v_pk_fma_f32 v[64:65], v[66:67], v[66:67], v[64:65]
	v_mov_b32_e32 v66, v68
	v_mov_b32_e32 v67, v126
	v_mov_b32_e32 v126, v69
	v_pk_add_f32 v[66:67], v[66:67], v[126:127]
	v_mov_b32_e32 v68, v64
	v_mov_b32_e32 v69, v128
	v_pk_add_f32 v[66:67], v[66:67], v[68:69]
	v_mov_b32_e32 v128, v65
	v_pk_add_f32 v[64:65], v[66:67], v[128:129]
	ds_bpermute_b32 v67, v148, v65
	ds_bpermute_b32 v66, v148, v64
	s_waitcnt lgkmcnt(0)
	v_pk_add_f32 v[64:65], v[64:65], v[66:67]
	ds_bpermute_b32 v67, v149, v65
	ds_bpermute_b32 v66, v149, v64
	s_waitcnt lgkmcnt(0)
	v_pk_add_f32 v[64:65], v[64:65], v[66:67]
	ds_bpermute_b32 v67, v150, v65
	ds_bpermute_b32 v66, v150, v64
	s_waitcnt lgkmcnt(0)
	v_pk_add_f32 v[64:65], v[64:65], v[66:67]
	ds_bpermute_b32 v67, v151, v65
	ds_bpermute_b32 v66, v151, v64
	s_waitcnt lgkmcnt(0)
	v_pk_add_f32 v[64:65], v[64:65], v[66:67]
	ds_bpermute_b32 v67, v152, v65
	ds_bpermute_b32 v66, v152, v64
	s_waitcnt lgkmcnt(0)
	v_pk_add_f32 v[64:65], v[64:65], v[66:67]
	ds_bpermute_b32 v67, v153, v65
	ds_bpermute_b32 v66, v153, v64
	s_waitcnt lgkmcnt(0)
	v_pk_add_f32 v[64:65], v[64:65], v[66:67]
	s_nop 0
	v_pk_fma_f32 v[88:89], v[64:65], s[10:11], v[88:89] op_sel_hi:[1,0,0]
	s_nop 0
	v_mul_f32_e32 v64, 0x4b800000, v89
	v_cmp_gt_f32_e64 s[0:1], s25, v89
	v_cmp_gt_f32_e32 vcc, s25, v88
	s_nop 0
	v_cndmask_b32_e64 v64, v89, v64, s[0:1]
	v_rsq_f32_e32 v64, v64
	s_nop 0
	v_mul_f32_e32 v65, 0x45800000, v64
	v_cndmask_b32_e64 v126, v64, v65, s[0:1]
	v_pk_mul_f32 v[64:65], v[126:127], v[114:115] op_sel_hi:[0,1]
	s_waitcnt vmcnt(9)
	v_pk_fma_f32 v[68:69], v[4:5], v[64:65], v[48:49]
	v_pk_mul_f32 v[48:49], v[126:127], v[94:95] op_sel_hi:[0,1]
	s_nop 0
	v_pk_fma_f32 v[70:71], v[6:7], v[48:49], v[50:51]
	v_pk_mul_f32 v[48:49], v[126:127], v[118:119] op_sel_hi:[0,1]
	s_waitcnt vmcnt(8)
	v_pk_fma_f32 v[64:65], v[0:1], v[48:49], v[52:53]
	v_pk_mul_f32 v[48:49], v[126:127], v[116:117] op_sel_hi:[0,1]
	s_nop 0
	v_pk_fma_f32 v[66:67], v[2:3], v[48:49], v[54:55]
	v_pk_mul_f32 v[48:49], v[126:127], v[124:125] op_sel_hi:[0,1]
	s_waitcnt vmcnt(7)
	v_pk_fma_f32 v[52:53], v[12:13], v[48:49], v[60:61]
	v_pk_mul_f32 v[48:49], v[126:127], v[122:123] op_sel_hi:[0,1]
	s_nop 0
	v_pk_fma_f32 v[54:55], v[14:15], v[48:49], v[62:63]
	v_pk_mul_f32 v[48:49], v[126:127], v[120:121] op_sel_hi:[0,1]
	s_waitcnt vmcnt(6)
	v_pk_fma_f32 v[48:49], v[8:9], v[48:49], v[56:57]
	v_mul_f32_e32 v56, 0x4b800000, v88
	v_cndmask_b32_e32 v56, v88, v56, vcc
	v_rsq_f32_e32 v56, v56
	v_pk_mul_f32 v[50:51], v[126:127], v[92:93] op_sel_hi:[0,1]
	s_nop 0
	v_pk_fma_f32 v[50:51], v[10:11], v[50:51], v[58:59]
	global_store_dwordx4 v[90:91], v[68:71], off
	v_mul_f32_e32 v57, 0x45800000, v56
	v_cndmask_b32_e32 v88, v56, v57, vcc
	v_pk_mul_f32 v[56:57], v[88:89], v[134:135] op_sel_hi:[0,1]
	s_waitcnt vmcnt(4)
	v_pk_fma_f32 v[60:61], v[4:5], v[56:57], v[72:73]
	v_pk_mul_f32 v[4:5], v[88:89], v[132:133] op_sel_hi:[0,1]
	s_nop 0
	v_pk_fma_f32 v[62:63], v[6:7], v[4:5], v[74:75]
	v_pk_mul_f32 v[4:5], v[88:89], v[138:139] op_sel_hi:[0,1]
	s_waitcnt vmcnt(3)
	v_pk_fma_f32 v[56:57], v[0:1], v[4:5], v[76:77]
	v_pk_mul_f32 v[0:1], v[88:89], v[136:137] op_sel_hi:[0,1]
	s_nop 0
	v_pk_fma_f32 v[58:59], v[2:3], v[0:1], v[78:79]
	v_pk_mul_f32 v[0:1], v[88:89], v[144:145] op_sel_hi:[0,1]
	s_waitcnt vmcnt(2)
	v_pk_fma_f32 v[4:5], v[12:13], v[0:1], v[80:81]
	v_pk_mul_f32 v[0:1], v[88:89], v[140:141] op_sel_hi:[0,1]
	s_nop 0
	v_pk_fma_f32 v[6:7], v[14:15], v[0:1], v[82:83]
	v_pk_mul_f32 v[0:1], v[88:89], v[146:147] op_sel_hi:[0,1]
	v_pk_mul_f32 v[2:3], v[88:89], v[142:143] op_sel_hi:[0,1]
	s_waitcnt vmcnt(1)
	v_pk_fma_f32 v[0:1], v[8:9], v[0:1], v[84:85]
	v_pk_fma_f32 v[2:3], v[10:11], v[2:3], v[86:87]
	s_andn2_b64 vcc, exec, s[16:17]
	global_store_dwordx4 v[90:91], v[64:67], off offset:1024
	global_store_dwordx4 v[90:91], v[52:55], off offset:2048
	global_store_dwordx4 v[90:91], v[48:51], off offset:3072
	global_store_dwordx4 v[130:131], v[60:63], off
	global_store_dwordx4 v[130:131], v[56:59], off offset:1024
	global_store_dwordx4 v[130:131], v[4:7], off offset:2048
	global_store_dwordx4 v[130:131], v[0:3], off offset:3072
	s_cbranch_vccnz .LBB0_478
	v_add_u32_e32 v10, 5, v105
	v_mov_b64_e32 v[8:9], s[4:5]
	v_mov_b32_e32 v14, v45
	v_mov_b32_e32 v15, v41
	v_mad_i64_i32 v[8:9], s[0:1], v10, s29, v[8:9]
	v_mov_b32_e32 v10, v44
	v_mov_b32_e32 v11, v40
	v_pk_mul_f32 v[14:15], v[14:15], v[14:15]
	v_lshl_add_u64 v[8:9], v[8:9], 0, v[176:177]
	v_pk_fma_f32 v[10:11], v[10:11], v[10:11], v[14:15]
	v_mov_b32_e32 v14, v46
	v_mov_b32_e32 v15, v42
	v_pk_fma_f32 v[10:11], v[14:15], v[14:15], v[10:11]
	v_mov_b32_e32 v14, v47
	v_mov_b32_e32 v15, v43
	v_pk_fma_f32 v[114:115], v[14:15], v[14:15], v[10:11]
	v_mov_b32_e32 v14, v29
	v_mov_b32_e32 v15, v37
	v_mov_b32_e32 v10, v28
	v_mov_b32_e32 v11, v36
	v_pk_mul_f32 v[14:15], v[14:15], v[14:15]
	s_movk_i32 s0, 0x1000
	v_pk_fma_f32 v[10:11], v[10:11], v[10:11], v[14:15]
	v_mov_b32_e32 v14, v30
	v_mov_b32_e32 v15, v38
	v_pk_fma_f32 v[10:11], v[14:15], v[14:15], v[10:11]
	v_mov_b32_e32 v14, v31
	v_mov_b32_e32 v15, v39
	v_pk_fma_f32 v[116:117], v[14:15], v[14:15], v[10:11]
	v_add_co_u32_e32 v14, vcc, s0, v8
	v_lshl_add_u64 v[12:13], v[8:9], 0, s[42:43]
	s_nop 0
	v_addc_co_u32_e32 v15, vcc, 0, v9, vcc
	global_load_dwordx4 v[84:87], v[8:9], off
	global_load_dwordx4 v[72:75], v[8:9], off offset:1024
	global_load_dwordx4 v[88:91], v[12:13], off offset:1024
	global_load_dwordx4 v[76:79], v[12:13], off offset:2048
	global_load_dwordx4 v[80:83], v[8:9], off offset:2048
	s_nop 0
	global_load_dwordx4 v[8:11], v[8:9], off offset:3072
	s_nop 0
	global_load_dwordx4 v[92:95], v[14:15], off
	s_nop 0
	global_load_dwordx4 v[12:15], v[12:13], off offset:3072
	v_mov_b32_e32 v120, v21
	v_mov_b32_e32 v121, v33
	v_mov_b32_e32 v118, v20
	v_mov_b32_e32 v119, v32
	v_pk_mul_f32 v[120:121], v[120:121], v[120:121]
	v_mov_b32_e32 v122, v17
	v_pk_fma_f32 v[118:119], v[118:119], v[118:119], v[120:121]
	v_mov_b32_e32 v120, v22
	v_mov_b32_e32 v121, v34
	v_pk_fma_f32 v[118:119], v[120:121], v[120:121], v[118:119]
	v_mov_b32_e32 v120, v23
	v_mov_b32_e32 v121, v35
	v_mov_b32_e32 v123, v25
	v_pk_fma_f32 v[118:119], v[120:121], v[120:121], v[118:119]
	v_mov_b32_e32 v120, v16
	v_mov_b32_e32 v121, v24
	v_pk_mul_f32 v[122:123], v[122:123], v[122:123]
	s_mov_b32 s0, 0x358637bd
	v_pk_fma_f32 v[120:121], v[120:121], v[120:121], v[122:123]
	v_mov_b32_e32 v122, v18
	v_mov_b32_e32 v123, v26
	v_pk_fma_f32 v[120:121], v[122:123], v[122:123], v[120:121]
	v_mov_b32_e32 v122, v19
	v_mov_b32_e32 v123, v27
	v_pk_fma_f32 v[120:121], v[122:123], v[122:123], v[120:121]
	v_mov_b32_e32 v122, v118
	v_mov_b32_e32 v123, v114
	v_mov_b32_e32 v114, v119
	v_pk_add_f32 v[114:115], v[122:123], v[114:115]
	v_mov_b32_e32 v118, v121
	v_mov_b32_e32 v119, v117
	v_pk_add_f32 v[114:115], v[118:119], v[114:115]
	v_mov_b32_e32 v121, v116
	v_pk_add_f32 v[114:115], v[120:121], v[114:115]
	ds_bpermute_b32 v117, v148, v115
	ds_bpermute_b32 v116, v148, v114
	v_lshl_add_u64 v[112:113], v[100:101], 0, v[112:113]
	s_waitcnt lgkmcnt(0)
	v_pk_add_f32 v[114:115], v[114:115], v[116:117]
	ds_bpermute_b32 v117, v149, v115
	ds_bpermute_b32 v116, v149, v114
	s_waitcnt lgkmcnt(0)
	v_pk_add_f32 v[114:115], v[114:115], v[116:117]
	ds_bpermute_b32 v117, v150, v115
	ds_bpermute_b32 v116, v150, v114
	s_waitcnt lgkmcnt(0)
	v_pk_add_f32 v[114:115], v[114:115], v[116:117]
	ds_bpermute_b32 v117, v151, v115
	ds_bpermute_b32 v116, v151, v114
	s_waitcnt lgkmcnt(0)
	v_pk_add_f32 v[114:115], v[114:115], v[116:117]
	ds_bpermute_b32 v117, v152, v115
	ds_bpermute_b32 v116, v152, v114
	s_waitcnt lgkmcnt(0)
	v_pk_add_f32 v[114:115], v[114:115], v[116:117]
	ds_bpermute_b32 v117, v153, v115
	ds_bpermute_b32 v116, v153, v114
	s_waitcnt lgkmcnt(0)
	v_pk_add_f32 v[114:115], v[114:115], v[116:117]
	v_mov_b64_e32 v[116:117], s[0:1]
	s_mov_b32 s0, 0x3a800000
	v_pk_fma_f32 v[114:115], v[114:115], s[0:1], v[116:117] op_sel_hi:[1,0,0]
	s_nop 0
	v_mul_f32_e32 v105, 0x4b800000, v115
	v_cmp_gt_f32_e32 vcc, s25, v115
	s_nop 1
	v_cndmask_b32_e32 v105, v115, v105, vcc
	v_rsq_f32_e32 v105, v105
	s_nop 0
	v_mul_f32_e32 v115, 0x45800000, v105
	v_cndmask_b32_e32 v118, v105, v115, vcc
	v_pk_mul_f32 v[44:45], v[44:45], v[118:119] op_sel_hi:[1,0]
	v_pk_mul_f32 v[46:47], v[46:47], v[118:119] op_sel_hi:[1,0]
	v_pk_mul_f32 v[36:37], v[36:37], v[118:119] op_sel_hi:[1,0]
	s_waitcnt vmcnt(1)
	v_pk_fma_f32 v[44:45], v[92:93], v[44:45], v[84:85]
	v_pk_fma_f32 v[46:47], v[94:95], v[46:47], v[86:87]
	v_pk_mul_f32 v[40:41], v[40:41], v[118:119] op_sel_hi:[1,0]
	v_pk_mul_f32 v[42:43], v[42:43], v[118:119] op_sel_hi:[1,0]
	v_pk_fma_f32 v[36:37], v[76:77], v[36:37], v[80:81]
	v_pk_mul_f32 v[38:39], v[38:39], v[118:119] op_sel_hi:[1,0]
	v_cvt_pk_bf16_f32 v44, v44, v45
	v_cvt_pk_bf16_f32 v45, v46, v47
	v_pk_fma_f32 v[40:41], v[88:89], v[40:41], v[72:73]
	v_pk_fma_f32 v[42:43], v[90:91], v[42:43], v[74:75]
	v_pk_fma_f32 v[38:39], v[78:79], v[38:39], v[82:83]
	v_cvt_pk_bf16_f32 v36, v36, v37
	v_cvt_pk_bf16_f32 v40, v40, v41
	v_cvt_pk_bf16_f32 v41, v42, v43
	v_cvt_pk_bf16_f32 v37, v38, v39
	global_store_dwordx2 v[112:113], v[44:45], off
	global_store_dwordx2 v[112:113], v[40:41], off offset:512
	global_store_dwordx2 v[112:113], v[36:37], off offset:1024
	v_mul_f32_e32 v36, 0x4b800000, v114
	v_cmp_gt_f32_e32 vcc, s25, v114
	v_pk_mul_f32 v[28:29], v[28:29], v[118:119] op_sel_hi:[1,0]
	v_pk_mul_f32 v[30:31], v[30:31], v[118:119] op_sel_hi:[1,0]
	v_cndmask_b32_e32 v36, v114, v36, vcc
	v_rsq_f32_e32 v36, v36
	s_waitcnt vmcnt(3)
	v_pk_fma_f32 v[28:29], v[12:13], v[28:29], v[8:9]
	v_pk_fma_f32 v[30:31], v[14:15], v[30:31], v[10:11]
	v_cvt_pk_bf16_f32 v28, v28, v29
	v_cvt_pk_bf16_f32 v29, v30, v31
	global_store_dwordx2 v[112:113], v[28:29], off offset:1536
	v_mul_f32_e32 v28, 0x45800000, v36
	v_mov_b32_e32 v38, v69
	v_mov_b32_e32 v39, v65
	v_cndmask_b32_e32 v28, v36, v28, vcc
	v_mov_b32_e32 v36, v68
	v_mov_b32_e32 v37, v64
	v_pk_mul_f32 v[38:39], v[38:39], v[38:39]
	v_mov_b32_e32 v40, v49
	v_pk_fma_f32 v[36:37], v[36:37], v[36:37], v[38:39]
	v_mov_b32_e32 v38, v70
	v_mov_b32_e32 v39, v66
	v_pk_fma_f32 v[36:37], v[38:39], v[38:39], v[36:37]
	v_mov_b32_e32 v38, v71
	v_mov_b32_e32 v39, v67
	v_mov_b32_e32 v41, v53
	v_pk_fma_f32 v[36:37], v[38:39], v[38:39], v[36:37]
	v_mov_b32_e32 v38, v48
	v_mov_b32_e32 v39, v52
	v_pk_mul_f32 v[40:41], v[40:41], v[40:41]
	v_mov_b32_e32 v42, v61
	v_pk_fma_f32 v[38:39], v[38:39], v[38:39], v[40:41]
	v_mov_b32_e32 v40, v50
	v_mov_b32_e32 v41, v54
	v_pk_fma_f32 v[38:39], v[40:41], v[40:41], v[38:39]
	v_mov_b32_e32 v40, v51
	v_mov_b32_e32 v41, v55
	v_mov_b32_e32 v43, v57
	v_pk_fma_f32 v[38:39], v[40:41], v[40:41], v[38:39]
	v_mov_b32_e32 v40, v60
	v_mov_b32_e32 v41, v56
	v_pk_mul_f32 v[42:43], v[42:43], v[42:43]
	v_mov_b32_e32 v44, v1
	v_pk_fma_f32 v[40:41], v[40:41], v[40:41], v[42:43]
	v_mov_b32_e32 v42, v62
	v_mov_b32_e32 v43, v58
	v_pk_fma_f32 v[40:41], v[42:43], v[42:43], v[40:41]
	v_mov_b32_e32 v42, v63
	v_mov_b32_e32 v43, v59
	v_mov_b32_e32 v45, v5
	v_pk_fma_f32 v[40:41], v[42:43], v[42:43], v[40:41]
	v_mov_b32_e32 v42, v0
	v_mov_b32_e32 v43, v4
	v_pk_mul_f32 v[44:45], v[44:45], v[44:45]
	v_pk_mul_f32 v[20:21], v[20:21], v[28:29] op_sel_hi:[1,0]
	v_pk_fma_f32 v[42:43], v[42:43], v[42:43], v[44:45]
	v_mov_b32_e32 v44, v2
	v_mov_b32_e32 v45, v6
	v_pk_fma_f32 v[42:43], v[44:45], v[44:45], v[42:43]
	v_mov_b32_e32 v44, v3
	v_mov_b32_e32 v45, v7
	v_pk_fma_f32 v[42:43], v[44:45], v[44:45], v[42:43]
	v_mov_b32_e32 v44, v40
	v_mov_b32_e32 v45, v36
	v_mov_b32_e32 v36, v41
	v_pk_add_f32 v[36:37], v[44:45], v[36:37]
	v_mov_b32_e32 v40, v43
	v_mov_b32_e32 v41, v39
	v_pk_add_f32 v[36:37], v[40:41], v[36:37]
	v_mov_b32_e32 v43, v38
	v_pk_add_f32 v[36:37], v[42:43], v[36:37]
	ds_bpermute_b32 v39, v148, v37
	ds_bpermute_b32 v38, v148, v36
	v_pk_mul_f32 v[22:23], v[22:23], v[28:29] op_sel_hi:[1,0]
	v_pk_fma_f32 v[20:21], v[92:93], v[20:21], v[84:85]
	v_pk_fma_f32 v[22:23], v[94:95], v[22:23], v[86:87]
	v_cvt_pk_bf16_f32 v20, v20, v21
	v_cvt_pk_bf16_f32 v21, v22, v23
	s_waitcnt lgkmcnt(0)
	v_pk_add_f32 v[22:23], v[36:37], v[38:39]
	ds_bpermute_b32 v37, v149, v23
	ds_bpermute_b32 v36, v149, v22
	v_lshl_add_u64 v[30:31], v[100:101], 0, v[110:111]
	global_store_dwordx2 v[30:31], v[20:21], off
	v_pk_mul_f32 v[20:21], v[32:33], v[28:29] op_sel_hi:[1,0]
	v_pk_mul_f32 v[32:33], v[34:35], v[28:29] op_sel_hi:[1,0]
	s_waitcnt lgkmcnt(0)
	v_pk_add_f32 v[22:23], v[22:23], v[36:37]
	ds_bpermute_b32 v35, v150, v23
	ds_bpermute_b32 v34, v150, v22
	v_pk_fma_f32 v[20:21], v[88:89], v[20:21], v[72:73]
	v_pk_fma_f32 v[32:33], v[90:91], v[32:33], v[74:75]
	v_cvt_pk_bf16_f32 v20, v20, v21
	v_cvt_pk_bf16_f32 v21, v32, v33
	global_store_dwordx2 v[30:31], v[20:21], off offset:512
	s_waitcnt lgkmcnt(0)
	v_pk_add_f32 v[20:21], v[22:23], v[34:35]
	ds_bpermute_b32 v23, v151, v21
	ds_bpermute_b32 v22, v151, v20
	v_pk_mul_f32 v[16:17], v[16:17], v[28:29] op_sel_hi:[1,0]
	v_pk_mul_f32 v[18:19], v[18:19], v[28:29] op_sel_hi:[1,0]
	v_pk_fma_f32 v[16:17], v[12:13], v[16:17], v[8:9]
	v_pk_mul_f32 v[24:25], v[24:25], v[28:29] op_sel_hi:[1,0]
	s_waitcnt lgkmcnt(0)
	v_pk_add_f32 v[20:21], v[20:21], v[22:23]
	ds_bpermute_b32 v23, v152, v21
	ds_bpermute_b32 v22, v152, v20
	v_cvt_pk_bf16_f32 v16, v16, v17
	v_pk_mul_f32 v[26:27], v[26:27], v[28:29] op_sel_hi:[1,0]
	v_pk_fma_f32 v[18:19], v[14:15], v[18:19], v[10:11]
	v_pk_fma_f32 v[24:25], v[76:77], v[24:25], v[80:81]
	s_waitcnt lgkmcnt(0)
	v_pk_add_f32 v[20:21], v[20:21], v[22:23]
	ds_bpermute_b32 v23, v153, v21
	ds_bpermute_b32 v22, v153, v20
	v_pk_fma_f32 v[26:27], v[78:79], v[26:27], v[82:83]
	v_cvt_pk_bf16_f32 v24, v24, v25
	v_cvt_pk_bf16_f32 v25, v26, v27
	global_store_dwordx2 v[30:31], v[24:25], off offset:1024
	s_waitcnt lgkmcnt(0)
	v_pk_add_f32 v[20:21], v[20:21], v[22:23]
	s_nop 0
	v_pk_fma_f32 v[20:21], v[20:21], s[0:1], v[116:117] op_sel_hi:[1,0,0]
	s_nop 0
	v_mul_f32_e32 v17, 0x4b800000, v21
	v_cmp_gt_f32_e32 vcc, s25, v21
	s_nop 1
	v_cndmask_b32_e32 v17, v21, v17, vcc
	v_rsq_f32_e32 v21, v17
	v_cvt_pk_bf16_f32 v17, v18, v19
	global_store_dwordx2 v[30:31], v[16:17], off offset:1536
	v_lshl_add_u64 v[16:17], v[100:101], 0, v[108:109]
	v_mul_f32_e32 v18, 0x45800000, v21
	v_cndmask_b32_e32 v18, v21, v18, vcc
	v_pk_mul_f32 v[22:23], v[68:69], v[18:19] op_sel_hi:[1,0]
	v_pk_mul_f32 v[24:25], v[70:71], v[18:19] op_sel_hi:[1,0]
	v_pk_fma_f32 v[22:23], v[92:93], v[22:23], v[84:85]
	v_pk_fma_f32 v[24:25], v[94:95], v[24:25], v[86:87]
	v_cvt_pk_bf16_f32 v22, v22, v23
	v_cvt_pk_bf16_f32 v23, v24, v25
	global_store_dwordx2 v[16:17], v[22:23], off
	v_pk_mul_f32 v[22:23], v[64:65], v[18:19] op_sel_hi:[1,0]
	v_pk_mul_f32 v[24:25], v[66:67], v[18:19] op_sel_hi:[1,0]
	v_pk_fma_f32 v[22:23], v[88:89], v[22:23], v[72:73]
	v_pk_fma_f32 v[24:25], v[90:91], v[24:25], v[74:75]
	v_cvt_pk_bf16_f32 v22, v22, v23
	v_cvt_pk_bf16_f32 v23, v24, v25
	global_store_dwordx2 v[16:17], v[22:23], off offset:512
	v_pk_mul_f32 v[22:23], v[52:53], v[18:19] op_sel_hi:[1,0]
	v_pk_mul_f32 v[24:25], v[54:55], v[18:19] op_sel_hi:[1,0]
	v_mul_f32_e32 v21, 0x4b800000, v20
	v_cmp_gt_f32_e32 vcc, s25, v20
	v_pk_fma_f32 v[22:23], v[76:77], v[22:23], v[80:81]
	v_pk_fma_f32 v[24:25], v[78:79], v[24:25], v[82:83]
	v_cndmask_b32_e32 v20, v20, v21, vcc
	v_cvt_pk_bf16_f32 v22, v22, v23
	v_cvt_pk_bf16_f32 v23, v24, v25
	v_rsq_f32_e32 v24, v20
	global_store_dwordx2 v[16:17], v[22:23], off offset:1024
	v_pk_mul_f32 v[22:23], v[48:49], v[18:19] op_sel_hi:[1,0]
	v_pk_mul_f32 v[18:19], v[50:51], v[18:19] op_sel_hi:[1,0]
	v_pk_fma_f32 v[22:23], v[12:13], v[22:23], v[8:9]
	v_pk_fma_f32 v[18:19], v[14:15], v[18:19], v[10:11]
	v_cvt_pk_bf16_f32 v20, v22, v23
	v_cvt_pk_bf16_f32 v21, v18, v19
	global_store_dwordx2 v[16:17], v[20:21], off offset:1536
	v_mul_f32_e32 v16, 0x45800000, v24
	v_cndmask_b32_e32 v16, v24, v16, vcc
	v_pk_mul_f32 v[20:21], v[60:61], v[16:17] op_sel_hi:[1,0]
	v_pk_mul_f32 v[22:23], v[62:63], v[16:17] op_sel_hi:[1,0]
	v_pk_fma_f32 v[20:21], v[92:93], v[20:21], v[84:85]
	v_pk_fma_f32 v[22:23], v[94:95], v[22:23], v[86:87]
	v_lshl_add_u64 v[18:19], v[100:101], 0, v[106:107]
	v_cvt_pk_bf16_f32 v20, v20, v21
	v_cvt_pk_bf16_f32 v21, v22, v23
	global_store_dwordx2 v[18:19], v[20:21], off
	v_pk_mul_f32 v[20:21], v[56:57], v[16:17] op_sel_hi:[1,0]
	v_pk_mul_f32 v[22:23], v[58:59], v[16:17] op_sel_hi:[1,0]
	v_pk_mul_f32 v[4:5], v[4:5], v[16:17] op_sel_hi:[1,0]
	v_pk_mul_f32 v[6:7], v[6:7], v[16:17] op_sel_hi:[1,0]
	v_pk_mul_f32 v[0:1], v[0:1], v[16:17] op_sel_hi:[1,0]
	v_pk_mul_f32 v[2:3], v[2:3], v[16:17] op_sel_hi:[1,0]
	v_pk_fma_f32 v[20:21], v[88:89], v[20:21], v[72:73]
	v_pk_fma_f32 v[22:23], v[90:91], v[22:23], v[74:75]
	v_pk_fma_f32 v[4:5], v[76:77], v[4:5], v[80:81]
	v_pk_fma_f32 v[6:7], v[78:79], v[6:7], v[82:83]
	v_pk_fma_f32 v[0:1], v[12:13], v[0:1], v[8:9]
	v_pk_fma_f32 v[2:3], v[14:15], v[2:3], v[10:11]
	v_cvt_pk_bf16_f32 v20, v20, v21
	v_cvt_pk_bf16_f32 v21, v22, v23
	v_cvt_pk_bf16_f32 v4, v4, v5
	v_cvt_pk_bf16_f32 v5, v6, v7
	v_cvt_pk_bf16_f32 v0, v0, v1
	v_cvt_pk_bf16_f32 v1, v2, v3
	global_store_dwordx2 v[18:19], v[20:21], off offset:512
	global_store_dwordx2 v[18:19], v[4:5], off offset:1024
	global_store_dwordx2 v[18:19], v[0:1], off offset:1536
	s_branch .LBB0_478

.LBB0_1057:
	v_add_u32_e32 v0, 0xfffff000, v104
	v_ashrrev_i32_e32 v1, 10, v0
	v_cmp_gt_i32_e32 vcc, s80, v97
	v_add_u32_e32 v1, 1, v1
	v_mov_b32_e32 v2, s60
	v_cndmask_b32_e64 v6, v1, 0, vcc
	v_mov_b32_e32 v1, s62
	v_readlane_b32 s0, v255, 20
	v_cndmask_b32_e32 v1, v1, v2, vcc
	v_mov_b32_e32 v2, s63
	v_mov_b32_e32 v3, s61
	v_readlane_b32 s1, v255, 21
	v_cndmask_b32_e32 v0, v0, v104, vcc
	v_cndmask_b32_e32 v2, v2, v3, vcc
	v_mov_b32_e32 v3, s1
	v_cndmask_b32_e64 v0, v104, v0, s[38:39]
	v_cndmask_b32_e64 v3, v3, v2, s[38:39]
	v_mov_b32_e32 v2, s0
	v_cndmask_b32_e64 v2, v2, v1, s[38:39]
	v_ashrrev_i32_e32 v1, 31, v0
	v_lshlrev_b64 v[0:1], 12, v[0:1]
	v_ashrrev_i32_e32 v105, 31, v104
	v_lshl_add_u64 v[0:1], v[2:3], 0, v[0:1]
	v_lshlrev_b32_e32 v176, 2, v96
	v_lshlrev_b64 v[112:113], 11, v[104:105]
	v_lshl_add_u64 v[64:65], v[0:1], 0, v[176:177]
	v_lshl_add_u64 v[0:1], v[98:99], 0, v[112:113]
	global_load_dwordx2 v[4:5], v[0:1], off
	global_load_dwordx2 v[8:9], v[0:1], off offset:512
	global_load_dwordx2 v[12:13], v[0:1], off offset:1024
	global_load_dwordx2 v[46:47], v[0:1], off offset:1536
	v_add_u32_e32 v44, 1, v104
	v_ashrrev_i32_e32 v45, 31, v44
	v_lshlrev_b64 v[110:111], 11, v[44:45]
	v_lshl_add_u64 v[0:1], v[98:99], 0, v[110:111]
	global_load_dwordx2 v[42:43], v[0:1], off
	global_load_dwordx2 v[40:41], v[0:1], off offset:512
	global_load_dwordx2 v[34:35], v[0:1], off offset:1024
	global_load_dwordx2 v[32:33], v[0:1], off offset:1536
	v_add_u32_e32 v60, 2, v104
	v_ashrrev_i32_e32 v61, 31, v60
	v_add_u32_e32 v68, 3, v104
	v_lshlrev_b64 v[108:109], 11, v[60:61]
	v_ashrrev_i32_e32 v69, 31, v68
	v_lshl_add_u64 v[0:1], v[98:99], 0, v[108:109]
	v_lshlrev_b64 v[106:107], 11, v[68:69]
	global_load_dwordx2 v[78:79], v[0:1], off
	global_load_dwordx2 v[74:75], v[0:1], off offset:512
	global_load_dwordx2 v[62:63], v[0:1], off offset:1024
	global_load_dwordx2 v[70:71], v[0:1], off offset:1536
	v_lshl_add_u64 v[0:1], v[98:99], 0, v[106:107]
	v_add_u32_e32 v154, s8, v6
	global_load_dwordx2 v[66:67], v[0:1], off
	global_load_dwordx2 v[72:73], v[0:1], off offset:512
	global_load_dwordx2 v[76:77], v[0:1], off offset:1024
	global_load_dwordx2 v[80:81], v[0:1], off offset:1536
	v_mul_hi_i32_i24_e32 v1, 0x3000, v154
	v_mul_i32_i24_e32 v0, 0x3000, v154
	v_lshl_add_u64 v[0:1], s[4:5], 0, v[0:1]
	v_lshl_add_u64 v[0:1], v[0:1], 0, v[176:177]
	s_mov_b64 s[0:1], 0x2000
	v_lshl_add_u64 v[14:15], v[0:1], 0, s[0:1]
	s_movk_i32 s1, 0x2000
	v_add_co_u32_e32 v0, vcc, s1, v0
	global_load_dwordx4 v[16:19], v[64:65], off
	s_nop 0
	v_addc_co_u32_e32 v1, vcc, 0, v1, vcc
	global_load_dwordx4 v[0:3], v[0:1], off
	v_lshlrev_b64 v[6:7], 12, v[104:105]
	v_lshl_add_u64 v[82:83], v[102:103], 0, v[6:7]
	s_movk_i32 s0, 0x1000
	v_add_co_u32_e32 v128, vcc, s0, v64
	v_lshlrev_b64 v[44:45], 12, v[44:45]
	s_nop 0
	v_addc_co_u32_e32 v129, vcc, 0, v65, vcc
	v_add_co_u32_e32 v118, vcc, s1, v64
	v_lshl_add_u64 v[86:87], v[102:103], 0, v[44:45]
	s_nop 0
	v_addc_co_u32_e32 v119, vcc, 0, v65, vcc
	s_mov_b32 s0, 0x358637bd
	s_mov_b32 s12, 0x3a800000
	s_waitcnt vmcnt(17)
	v_and_b32_e32 v39, 0xffff0000, v4
	s_waitcnt vmcnt(16)
	v_and_b32_e32 v91, 0xffff0000, v8
	v_lshlrev_b32_e32 v38, 16, v4
	v_lshlrev_b32_e32 v90, 16, v8
	v_mov_b32_e32 v26, v39
	v_mov_b32_e32 v27, v91
	v_lshlrev_b32_e32 v36, 16, v5
	v_lshlrev_b32_e32 v88, 16, v9
	v_mov_b32_e32 v24, v38
	v_mov_b32_e32 v25, v90
	v_pk_mul_f32 v[26:27], v[26:27], v[26:27]
	v_and_b32_e32 v37, 0xffff0000, v5
	global_load_dwordx4 v[20:23], v[64:65], off offset:1024
	global_load_dwordx4 v[4:7], v[14:15], off offset:1024
	v_and_b32_e32 v89, 0xffff0000, v9
	v_mov_b32_e32 v8, v36
	v_mov_b32_e32 v9, v88
	v_pk_fma_f32 v[24:25], v[24:25], v[24:25], v[26:27]
	v_mov_b32_e32 v10, v37
	v_mov_b32_e32 v11, v89
	v_pk_fma_f32 v[8:9], v[8:9], v[8:9], v[24:25]
	s_waitcnt vmcnt(17)
	v_lshlrev_b32_e32 v92, 16, v13
	v_pk_fma_f32 v[84:85], v[10:11], v[10:11], v[8:9]
	global_load_dwordx4 v[24:27], v[64:65], off offset:2048
	global_load_dwordx4 v[8:11], v[14:15], off offset:2048
	v_and_b32_e32 v93, 0xffff0000, v13
	v_lshlrev_b32_e32 v94, 16, v12
	v_and_b32_e32 v95, 0xffff0000, v12
	global_load_dwordx4 v[28:31], v[64:65], off offset:3072
	s_nop 0
	global_load_dwordx4 v[12:15], v[14:15], off offset:3072
	s_waitcnt vmcnt(20)
	v_and_b32_e32 v117, 0xffff0000, v46
	v_lshlrev_b32_e32 v116, 16, v46
	v_mov_b32_e32 v52, v95
	v_mov_b32_e32 v53, v117
	v_lshlrev_b32_e32 v114, 16, v47
	v_mov_b32_e32 v50, v94
	v_mov_b32_e32 v51, v116
	v_pk_mul_f32 v[52:53], v[52:53], v[52:53]
	v_and_b32_e32 v115, 0xffff0000, v47
	v_mov_b32_e32 v46, v92
	v_mov_b32_e32 v47, v114
	v_pk_fma_f32 v[50:51], v[50:51], v[50:51], v[52:53]
	v_mov_b32_e32 v48, v93
	v_mov_b32_e32 v49, v115
	v_pk_fma_f32 v[46:47], v[46:47], v[46:47], v[50:51]
	s_waitcnt vmcnt(19)
	v_and_b32_e32 v123, 0xffff0000, v42
	v_pk_fma_f32 v[46:47], v[48:49], v[48:49], v[46:47]
	global_load_dwordx4 v[48:51], v[118:119], off offset:-4096
	global_load_dwordx4 v[52:55], v[128:129], off offset:1024
	s_waitcnt vmcnt(20)
	v_and_b32_e32 v127, 0xffff0000, v40
	v_lshlrev_b32_e32 v122, 16, v42
	v_lshlrev_b32_e32 v126, 16, v40
	v_mov_b32_e32 v56, v123
	v_mov_b32_e32 v57, v127
	v_mov_b32_e32 v44, v122
	v_mov_b32_e32 v45, v126
	v_pk_mul_f32 v[56:57], v[56:57], v[56:57]
	v_lshlrev_b32_e32 v120, 16, v43
	v_pk_fma_f32 v[44:45], v[44:45], v[44:45], v[56:57]
	global_load_dwordx4 v[56:59], v[128:129], off offset:2048
	v_lshlrev_b32_e32 v124, 16, v41
	v_and_b32_e32 v121, 0xffff0000, v43
	v_and_b32_e32 v125, 0xffff0000, v41
	v_mov_b32_e32 v40, v120
	v_mov_b32_e32 v41, v124
	s_waitcnt vmcnt(20)
	v_and_b32_e32 v135, 0xffff0000, v34
	s_waitcnt vmcnt(19)
	v_and_b32_e32 v139, 0xffff0000, v32
	v_mov_b32_e32 v42, v121
	v_mov_b32_e32 v43, v125
	v_pk_fma_f32 v[40:41], v[40:41], v[40:41], v[44:45]
	v_lshlrev_b32_e32 v134, 16, v34
	v_lshlrev_b32_e32 v138, 16, v32
	v_mov_b32_e32 v44, v135
	v_mov_b32_e32 v45, v139
	v_pk_fma_f32 v[40:41], v[42:43], v[42:43], v[40:41]
	v_lshlrev_b32_e32 v132, 16, v35
	v_lshlrev_b32_e32 v136, 16, v33
	v_mov_b32_e32 v42, v134
	v_mov_b32_e32 v43, v138
	v_pk_mul_f32 v[44:45], v[44:45], v[44:45]
	v_and_b32_e32 v133, 0xffff0000, v35
	v_and_b32_e32 v137, 0xffff0000, v33
	v_mov_b32_e32 v32, v132
	v_mov_b32_e32 v33, v136
	v_pk_fma_f32 v[42:43], v[42:43], v[42:43], v[44:45]
	v_mov_b32_e32 v34, v133
	v_mov_b32_e32 v35, v137
	v_pk_fma_f32 v[32:33], v[32:33], v[32:33], v[42:43]
	global_load_dwordx4 v[128:131], v[128:129], off offset:3072
	v_pk_fma_f32 v[32:33], v[34:35], v[34:35], v[32:33]
	v_mov_b32_e32 v34, v40
	v_mov_b32_e32 v35, v84
	v_mov_b32_e32 v84, v41
	v_pk_add_f32 v[34:35], v[34:35], v[84:85]
	v_mov_b32_e32 v40, v32
	v_mov_b32_e32 v41, v46
	v_pk_add_f32 v[34:35], v[34:35], v[40:41]
	v_mov_b32_e32 v46, v33
	v_pk_add_f32 v[32:33], v[34:35], v[46:47]
	ds_bpermute_b32 v35, v148, v33
	ds_bpermute_b32 v34, v148, v32
	v_mov_b64_e32 v[84:85], s[0:1]
	s_waitcnt vmcnt(12)
	v_and_b32_e32 v147, 0xffff0000, v80
	v_lshlrev_b32_e32 v146, 16, v80
	v_mov_b32_e32 v161, v147
	s_waitcnt lgkmcnt(0)
	v_pk_add_f32 v[32:33], v[32:33], v[34:35]
	ds_bpermute_b32 v35, v149, v33
	ds_bpermute_b32 v34, v149, v32
	v_lshlrev_b32_e32 v144, 16, v81
	v_mov_b32_e32 v159, v146
	v_and_b32_e32 v145, 0xffff0000, v81
	v_mov_b32_e32 v81, v144
	s_waitcnt lgkmcnt(0)
	v_pk_add_f32 v[32:33], v[32:33], v[34:35]
	ds_bpermute_b32 v35, v150, v33
	ds_bpermute_b32 v34, v150, v32
	v_mov_b32_e32 v157, v145
	s_waitcnt lgkmcnt(0)
	v_pk_add_f32 v[32:33], v[32:33], v[34:35]
	ds_bpermute_b32 v35, v151, v33
	ds_bpermute_b32 v34, v151, v32
	s_waitcnt lgkmcnt(0)
	v_pk_add_f32 v[32:33], v[32:33], v[34:35]
	ds_bpermute_b32 v35, v152, v33
	ds_bpermute_b32 v34, v152, v32
	s_waitcnt lgkmcnt(0)
	v_pk_add_f32 v[32:33], v[32:33], v[34:35]
	ds_bpermute_b32 v35, v153, v33
	ds_bpermute_b32 v34, v153, v32
	s_waitcnt lgkmcnt(0)
	v_pk_add_f32 v[32:33], v[32:33], v[34:35]
	s_nop 0
	v_pk_fma_f32 v[140:141], v[32:33], s[12:13], v[84:85] op_sel_hi:[1,0,0]
	s_nop 0
	v_mul_f32_e32 v32, 0x4b800000, v141
	v_cmp_gt_f32_e64 s[0:1], s25, v141
	v_cmp_gt_f32_e32 vcc, s25, v140
	s_nop 0
	v_cndmask_b32_e64 v32, v141, v32, s[0:1]
	v_rsq_f32_e32 v32, v32
	s_nop 0
	v_mul_f32_e32 v33, 0x45800000, v32
	v_cndmask_b32_e64 v34, v32, v33, s[0:1]
	v_pk_mul_f32 v[32:33], v[34:35], v[38:39] op_sel_hi:[0,1]
	s_waitcnt vmcnt(10)
	v_pk_fma_f32 v[44:45], v[0:1], v[32:33], v[16:17]
	v_pk_mul_f32 v[16:17], v[34:35], v[36:37] op_sel_hi:[0,1]
	s_nop 0
	v_pk_fma_f32 v[46:47], v[2:3], v[16:17], v[18:19]
	v_pk_mul_f32 v[16:17], v[34:35], v[90:91] op_sel_hi:[0,1]
	s_waitcnt vmcnt(8)
	v_pk_fma_f32 v[40:41], v[4:5], v[16:17], v[20:21]
	v_pk_mul_f32 v[16:17], v[34:35], v[88:89] op_sel_hi:[0,1]
	s_nop 0
	v_pk_fma_f32 v[42:43], v[6:7], v[16:17], v[22:23]
	v_pk_mul_f32 v[16:17], v[34:35], v[94:95] op_sel_hi:[0,1]
	s_waitcnt vmcnt(6)
	v_pk_fma_f32 v[36:37], v[8:9], v[16:17], v[24:25]
	v_pk_mul_f32 v[16:17], v[34:35], v[92:93] op_sel_hi:[0,1]
	s_nop 0
	v_pk_fma_f32 v[38:39], v[10:11], v[16:17], v[26:27]
	v_pk_mul_f32 v[16:17], v[34:35], v[116:117] op_sel_hi:[0,1]
	s_waitcnt vmcnt(4)
	v_pk_fma_f32 v[32:33], v[12:13], v[16:17], v[28:29]
	v_pk_mul_f32 v[16:17], v[34:35], v[114:115] op_sel_hi:[0,1]
	s_nop 0
	v_pk_fma_f32 v[34:35], v[14:15], v[16:17], v[30:31]
	v_mul_f32_e32 v16, 0x4b800000, v140
	v_cndmask_b32_e32 v16, v140, v16, vcc
	v_rsq_f32_e32 v16, v16
	v_and_b32_e32 v95, 0xffff0000, v78
	v_and_b32_e32 v115, 0xffff0000, v74
	v_lshlrev_b32_e32 v94, 16, v78
	v_mul_f32_e32 v17, 0x45800000, v16
	v_cndmask_b32_e32 v18, v16, v17, vcc
	v_pk_mul_f32 v[16:17], v[18:19], v[122:123] op_sel_hi:[0,1]
	s_waitcnt vmcnt(3)
	v_pk_fma_f32 v[28:29], v[0:1], v[16:17], v[48:49]
	v_pk_mul_f32 v[16:17], v[18:19], v[120:121] op_sel_hi:[0,1]
	s_nop 0
	v_pk_fma_f32 v[30:31], v[2:3], v[16:17], v[50:51]
	v_pk_mul_f32 v[16:17], v[18:19], v[126:127] op_sel_hi:[0,1]
	s_waitcnt vmcnt(2)
	v_pk_fma_f32 v[24:25], v[4:5], v[16:17], v[52:53]
	v_pk_mul_f32 v[16:17], v[18:19], v[124:125] op_sel_hi:[0,1]
	global_load_dwordx4 v[48:51], v[118:119], off
	v_lshlrev_b32_e32 v92, 16, v75
	v_and_b32_e32 v93, 0xffff0000, v75
	v_lshlrev_b32_e32 v114, 16, v74
	v_mov_b32_e32 v74, v95
	v_mov_b32_e32 v75, v115
	v_pk_fma_f32 v[26:27], v[6:7], v[16:17], v[54:55]
	v_pk_mul_f32 v[16:17], v[18:19], v[134:135] op_sel_hi:[0,1]
	v_lshlrev_b64 v[52:53], 12, v[60:61]
	v_lshlrev_b32_e32 v90, 16, v79
	v_mov_b32_e32 v60, v94
	v_mov_b32_e32 v61, v114
	v_pk_mul_f32 v[74:75], v[74:75], v[74:75]
	s_waitcnt vmcnt(2)
	v_pk_fma_f32 v[20:21], v[8:9], v[16:17], v[56:57]
	v_pk_mul_f32 v[16:17], v[18:19], v[132:133] op_sel_hi:[0,1]
	v_and_b32_e32 v91, 0xffff0000, v79
	v_lshl_add_u64 v[88:89], v[102:103], 0, v[52:53]
	global_load_dwordx4 v[52:55], v[118:119], off offset:1024
	v_mov_b32_e32 v56, v90
	v_mov_b32_e32 v57, v92
	v_pk_fma_f32 v[60:61], v[60:61], v[60:61], v[74:75]
	v_pk_fma_f32 v[22:23], v[10:11], v[16:17], v[58:59]
	v_mov_b32_e32 v58, v91
	v_mov_b32_e32 v59, v93
	v_pk_fma_f32 v[56:57], v[56:57], v[56:57], v[60:61]
	v_and_b32_e32 v121, 0xffff0000, v62
	v_pk_fma_f32 v[126:127], v[58:59], v[58:59], v[56:57]
	global_load_dwordx4 v[56:59], v[118:119], off offset:2048
	v_and_b32_e32 v123, 0xffff0000, v70
	v_lshlrev_b32_e32 v120, 16, v62
	v_lshlrev_b32_e32 v122, 16, v70
	v_mov_b32_e32 v124, v121
	v_mov_b32_e32 v125, v123
	v_lshlrev_b32_e32 v116, 16, v63
	v_and_b32_e32 v117, 0xffff0000, v63
	global_load_dwordx4 v[60:63], v[118:119], off offset:3072
	v_lshlrev_b32_e32 v118, 16, v71
	v_mov_b32_e32 v78, v120
	v_mov_b32_e32 v79, v122
	v_pk_mul_f32 v[124:125], v[124:125], v[124:125]
	v_and_b32_e32 v119, 0xffff0000, v71
	v_mov_b32_e32 v70, v116
	v_mov_b32_e32 v71, v118
	v_pk_fma_f32 v[78:79], v[78:79], v[78:79], v[124:125]
	v_pk_mul_f32 v[16:17], v[18:19], v[138:139] op_sel_hi:[0,1]
	v_pk_fma_f32 v[70:71], v[70:71], v[70:71], v[78:79]
	v_add_co_u32_e32 v78, vcc, s29, v64
	v_pk_mul_f32 v[18:19], v[18:19], v[136:137] op_sel_hi:[0,1]
	v_mov_b32_e32 v74, v117
	v_mov_b32_e32 v75, v119
	v_addc_co_u32_e32 v79, vcc, 0, v65, vcc
	v_and_b32_e32 v137, 0xffff0000, v66
	v_and_b32_e32 v135, 0xffff0000, v72
	s_waitcnt vmcnt(4)
	v_pk_fma_f32 v[16:17], v[12:13], v[16:17], v[128:129]
	v_pk_fma_f32 v[128:129], v[74:75], v[74:75], v[70:71]
	v_lshlrev_b64 v[74:75], 12, v[68:69]
	global_load_dwordx4 v[68:71], v[78:79], off
	v_lshlrev_b32_e32 v136, 16, v66
	v_lshlrev_b32_e32 v134, 16, v72
	v_mov_b32_e32 v140, v137
	v_mov_b32_e32 v141, v135
	v_pk_fma_f32 v[18:19], v[14:15], v[18:19], v[130:131]
	v_lshlrev_b32_e32 v132, 16, v67
	v_lshlrev_b32_e32 v130, 16, v73
	v_mov_b32_e32 v138, v136
	v_mov_b32_e32 v139, v134
	v_pk_mul_f32 v[140:141], v[140:141], v[140:141]
	v_and_b32_e32 v133, 0xffff0000, v67
	global_load_dwordx4 v[64:67], v[78:79], off offset:1024
	v_and_b32_e32 v131, 0xffff0000, v73
	v_mov_b32_e32 v72, v132
	v_mov_b32_e32 v73, v130
	v_pk_fma_f32 v[138:139], v[138:139], v[138:139], v[140:141]
	v_lshl_add_u64 v[124:125], v[102:103], 0, v[74:75]
	v_mov_b32_e32 v74, v133
	v_mov_b32_e32 v75, v131
	v_pk_fma_f32 v[72:73], v[72:73], v[72:73], v[138:139]
	v_lshlrev_b32_e32 v138, 16, v77
	v_pk_fma_f32 v[142:143], v[74:75], v[74:75], v[72:73]
	global_load_dwordx4 v[72:75], v[78:79], off offset:2048
	v_and_b32_e32 v139, 0xffff0000, v77
	v_lshlrev_b32_e32 v140, 16, v76
	v_and_b32_e32 v141, 0xffff0000, v76
	global_load_dwordx4 v[76:79], v[78:79], off offset:3072
	v_mov_b32_e32 v160, v141
	v_mov_b32_e32 v158, v140
	v_pk_mul_f32 v[160:161], v[160:161], v[160:161]
	v_mov_b32_e32 v80, v138
	v_pk_fma_f32 v[158:159], v[158:159], v[158:159], v[160:161]
	v_mov_b32_e32 v156, v139
	v_pk_fma_f32 v[80:81], v[80:81], v[80:81], v[158:159]
	global_store_dwordx4 v[82:83], v[44:47], off
	global_store_dwordx4 v[82:83], v[40:43], off offset:1024
	global_store_dwordx4 v[82:83], v[36:39], off offset:2048
	global_store_dwordx4 v[82:83], v[32:35], off offset:3072
	global_store_dwordx4 v[86:87], v[28:31], off
	global_store_dwordx4 v[86:87], v[24:27], off offset:1024
	global_store_dwordx4 v[86:87], v[20:23], off offset:2048
	global_store_dwordx4 v[86:87], v[16:19], off offset:3072
	v_pk_fma_f32 v[80:81], v[156:157], v[156:157], v[80:81]
	v_mov_b32_e32 v82, v142
	v_mov_b32_e32 v83, v126
	v_mov_b32_e32 v126, v143
	v_pk_add_f32 v[82:83], v[82:83], v[126:127]
	v_mov_b32_e32 v86, v80
	v_mov_b32_e32 v87, v128
	v_pk_add_f32 v[82:83], v[82:83], v[86:87]
	v_mov_b32_e32 v128, v81
	v_pk_add_f32 v[80:81], v[82:83], v[128:129]
	ds_bpermute_b32 v83, v148, v81
	ds_bpermute_b32 v82, v148, v80
	s_waitcnt lgkmcnt(0)
	v_pk_add_f32 v[80:81], v[80:81], v[82:83]
	ds_bpermute_b32 v83, v149, v81
	ds_bpermute_b32 v82, v149, v80
	s_waitcnt lgkmcnt(0)
	v_pk_add_f32 v[80:81], v[80:81], v[82:83]
	ds_bpermute_b32 v83, v150, v81
	ds_bpermute_b32 v82, v150, v80
	s_waitcnt lgkmcnt(0)
	v_pk_add_f32 v[80:81], v[80:81], v[82:83]
	ds_bpermute_b32 v83, v151, v81
	ds_bpermute_b32 v82, v151, v80
	s_waitcnt lgkmcnt(0)
	v_pk_add_f32 v[80:81], v[80:81], v[82:83]
	ds_bpermute_b32 v83, v152, v81
	ds_bpermute_b32 v82, v152, v80
	s_waitcnt lgkmcnt(0)
	v_pk_add_f32 v[80:81], v[80:81], v[82:83]
	ds_bpermute_b32 v83, v153, v81
	ds_bpermute_b32 v82, v153, v80
	s_waitcnt lgkmcnt(0)
	v_pk_add_f32 v[80:81], v[80:81], v[82:83]
	s_nop 0
	v_pk_fma_f32 v[126:127], v[80:81], s[12:13], v[84:85] op_sel_hi:[1,0,0]
	s_nop 0
	v_mul_f32_e32 v80, 0x4b800000, v127
	v_cmp_gt_f32_e64 s[0:1], s25, v127
	v_cmp_gt_f32_e32 vcc, s25, v126
	s_nop 0
	v_cndmask_b32_e64 v80, v127, v80, s[0:1]
	v_rsq_f32_e32 v80, v80
	s_nop 0
	v_mul_f32_e32 v81, 0x45800000, v80
	v_cndmask_b32_e64 v128, v80, v81, s[0:1]
	v_pk_mul_f32 v[80:81], v[128:129], v[94:95] op_sel_hi:[0,1]
	s_waitcnt vmcnt(15)
	v_pk_fma_f32 v[84:85], v[0:1], v[80:81], v[48:49]
	v_pk_mul_f32 v[48:49], v[128:129], v[90:91] op_sel_hi:[0,1]
	s_nop 0
	v_pk_fma_f32 v[86:87], v[2:3], v[48:49], v[50:51]
	v_pk_mul_f32 v[48:49], v[128:129], v[114:115] op_sel_hi:[0,1]
	s_waitcnt vmcnt(14)
	v_pk_fma_f32 v[80:81], v[4:5], v[48:49], v[52:53]
	v_pk_mul_f32 v[48:49], v[128:129], v[92:93] op_sel_hi:[0,1]
	s_nop 0
	v_pk_fma_f32 v[82:83], v[6:7], v[48:49], v[54:55]
	v_pk_mul_f32 v[48:49], v[128:129], v[120:121] op_sel_hi:[0,1]
	s_waitcnt vmcnt(13)
	v_pk_fma_f32 v[52:53], v[8:9], v[48:49], v[56:57]
	v_mul_f32_e32 v56, 0x4b800000, v126
	v_cndmask_b32_e32 v56, v126, v56, vcc
	v_rsq_f32_e32 v56, v56
	v_pk_mul_f32 v[48:49], v[128:129], v[116:117] op_sel_hi:[0,1]
	s_nop 0
	v_pk_fma_f32 v[54:55], v[10:11], v[48:49], v[58:59]
	v_pk_mul_f32 v[48:49], v[128:129], v[122:123] op_sel_hi:[0,1]
	v_pk_mul_f32 v[50:51], v[128:129], v[118:119] op_sel_hi:[0,1]
	v_mul_f32_e32 v57, 0x45800000, v56
	s_waitcnt vmcnt(12)
	v_pk_fma_f32 v[48:49], v[12:13], v[48:49], v[60:61]
	v_pk_fma_f32 v[50:51], v[14:15], v[50:51], v[62:63]
	global_store_dwordx4 v[88:89], v[84:87], off
	global_store_dwordx4 v[88:89], v[80:83], off offset:1024
	global_store_dwordx4 v[88:89], v[52:55], off offset:2048
	global_store_dwordx4 v[88:89], v[48:51], off offset:3072
	v_cndmask_b32_e32 v88, v56, v57, vcc
	v_pk_mul_f32 v[56:57], v[88:89], v[136:137] op_sel_hi:[0,1]
	s_waitcnt vmcnt(15)
	v_pk_fma_f32 v[60:61], v[0:1], v[56:57], v[68:69]
	v_pk_mul_f32 v[0:1], v[88:89], v[132:133] op_sel_hi:[0,1]
	s_nop 0
	v_pk_fma_f32 v[62:63], v[2:3], v[0:1], v[70:71]
	v_pk_mul_f32 v[0:1], v[88:89], v[134:135] op_sel_hi:[0,1]
	s_waitcnt vmcnt(14)
	v_pk_fma_f32 v[56:57], v[4:5], v[0:1], v[64:65]
	v_pk_mul_f32 v[0:1], v[88:89], v[130:131] op_sel_hi:[0,1]
	s_nop 0
	v_pk_fma_f32 v[58:59], v[6:7], v[0:1], v[66:67]
	v_pk_mul_f32 v[0:1], v[88:89], v[140:141] op_sel_hi:[0,1]
	s_waitcnt vmcnt(13)
	v_pk_fma_f32 v[4:5], v[8:9], v[0:1], v[72:73]
	v_pk_mul_f32 v[0:1], v[88:89], v[138:139] op_sel_hi:[0,1]
	s_nop 0
	v_pk_fma_f32 v[6:7], v[10:11], v[0:1], v[74:75]
	v_pk_mul_f32 v[0:1], v[88:89], v[146:147] op_sel_hi:[0,1]
	v_pk_mul_f32 v[2:3], v[88:89], v[144:145] op_sel_hi:[0,1]
	s_waitcnt vmcnt(12)
	v_pk_fma_f32 v[0:1], v[12:13], v[0:1], v[76:77]
	v_pk_fma_f32 v[2:3], v[14:15], v[2:3], v[78:79]
	s_andn2_b64 vcc, exec, s[16:17]
	global_store_dwordx4 v[124:125], v[60:63], off
	global_store_dwordx4 v[124:125], v[56:59], off offset:1024
	global_store_dwordx4 v[124:125], v[4:7], off offset:2048
	global_store_dwordx4 v[124:125], v[0:3], off offset:3072
	s_cbranch_vccnz .LBB0_1056
	v_add_u32_e32 v10, 5, v154
	v_mov_b64_e32 v[8:9], s[4:5]
	v_mov_b32_e32 v14, v45
	v_mov_b32_e32 v15, v41
	v_mad_i64_i32 v[8:9], s[0:1], v10, s29, v[8:9]
	v_mov_b32_e32 v10, v44
	v_mov_b32_e32 v11, v40
	v_pk_mul_f32 v[14:15], v[14:15], v[14:15]
	v_lshl_add_u64 v[8:9], v[8:9], 0, v[176:177]
	v_pk_fma_f32 v[10:11], v[10:11], v[10:11], v[14:15]
	v_mov_b32_e32 v14, v46
	v_mov_b32_e32 v15, v42
	v_pk_fma_f32 v[10:11], v[14:15], v[14:15], v[10:11]
	v_mov_b32_e32 v14, v47
	v_mov_b32_e32 v15, v43
	v_pk_fma_f32 v[114:115], v[14:15], v[14:15], v[10:11]
	v_mov_b32_e32 v14, v33
	v_mov_b32_e32 v15, v37
	v_mov_b32_e32 v10, v32
	v_mov_b32_e32 v11, v36
	v_pk_mul_f32 v[14:15], v[14:15], v[14:15]
	s_movk_i32 s0, 0x1000
	v_pk_fma_f32 v[10:11], v[10:11], v[10:11], v[14:15]
	v_mov_b32_e32 v14, v34
	v_mov_b32_e32 v15, v38
	v_pk_fma_f32 v[10:11], v[14:15], v[14:15], v[10:11]
	v_mov_b32_e32 v14, v35
	v_mov_b32_e32 v15, v39
	v_pk_fma_f32 v[116:117], v[14:15], v[14:15], v[10:11]
	v_add_co_u32_e32 v14, vcc, s0, v8
	v_lshl_add_u64 v[12:13], v[8:9], 0, s[42:43]
	s_nop 0
	v_addc_co_u32_e32 v15, vcc, 0, v9, vcc
	global_load_dwordx4 v[76:79], v[8:9], off
	global_load_dwordx4 v[64:67], v[8:9], off offset:1024
	global_load_dwordx4 v[88:91], v[12:13], off offset:1024
	global_load_dwordx4 v[68:71], v[12:13], off offset:2048
	global_load_dwordx4 v[72:75], v[8:9], off offset:2048
	s_nop 0
	global_load_dwordx4 v[8:11], v[8:9], off offset:3072
	s_nop 0
	global_load_dwordx4 v[92:95], v[14:15], off
	s_nop 0
	global_load_dwordx4 v[12:15], v[12:13], off offset:3072
	v_mov_b32_e32 v120, v29
	v_mov_b32_e32 v121, v25
	v_mov_b32_e32 v118, v28
	v_mov_b32_e32 v119, v24
	v_pk_mul_f32 v[120:121], v[120:121], v[120:121]
	v_mov_b32_e32 v122, v17
	v_pk_fma_f32 v[118:119], v[118:119], v[118:119], v[120:121]
	v_mov_b32_e32 v120, v30
	v_mov_b32_e32 v121, v26
	v_pk_fma_f32 v[118:119], v[120:121], v[120:121], v[118:119]
	v_mov_b32_e32 v120, v31
	v_mov_b32_e32 v121, v27
	v_mov_b32_e32 v123, v21
	v_pk_fma_f32 v[118:119], v[120:121], v[120:121], v[118:119]
	v_mov_b32_e32 v120, v16
	v_mov_b32_e32 v121, v20
	v_pk_mul_f32 v[122:123], v[122:123], v[122:123]
	s_mov_b32 s0, 0x358637bd
	v_pk_fma_f32 v[120:121], v[120:121], v[120:121], v[122:123]
	v_mov_b32_e32 v122, v18
	v_mov_b32_e32 v123, v22
	v_pk_fma_f32 v[120:121], v[122:123], v[122:123], v[120:121]
	v_mov_b32_e32 v122, v19
	v_mov_b32_e32 v123, v23
	v_pk_fma_f32 v[120:121], v[122:123], v[122:123], v[120:121]
	v_mov_b32_e32 v122, v118
	v_mov_b32_e32 v123, v114
	v_mov_b32_e32 v114, v119
	v_pk_add_f32 v[114:115], v[122:123], v[114:115]
	v_mov_b32_e32 v118, v121
	v_mov_b32_e32 v119, v117
	v_pk_add_f32 v[114:115], v[118:119], v[114:115]
	v_mov_b32_e32 v121, v116
	v_pk_add_f32 v[114:115], v[120:121], v[114:115]
	ds_bpermute_b32 v117, v148, v115
	ds_bpermute_b32 v116, v148, v114
	v_lshl_add_u64 v[112:113], v[100:101], 0, v[112:113]
	s_waitcnt lgkmcnt(0)
	v_pk_add_f32 v[114:115], v[114:115], v[116:117]
	ds_bpermute_b32 v117, v149, v115
	ds_bpermute_b32 v116, v149, v114
	s_waitcnt lgkmcnt(0)
	v_pk_add_f32 v[114:115], v[114:115], v[116:117]
	ds_bpermute_b32 v117, v150, v115
	ds_bpermute_b32 v116, v150, v114
	s_waitcnt lgkmcnt(0)
	v_pk_add_f32 v[114:115], v[114:115], v[116:117]
	ds_bpermute_b32 v117, v151, v115
	ds_bpermute_b32 v116, v151, v114
	s_waitcnt lgkmcnt(0)
	v_pk_add_f32 v[114:115], v[114:115], v[116:117]
	ds_bpermute_b32 v117, v152, v115
	ds_bpermute_b32 v116, v152, v114
	s_waitcnt lgkmcnt(0)
	v_pk_add_f32 v[114:115], v[114:115], v[116:117]
	ds_bpermute_b32 v117, v153, v115
	ds_bpermute_b32 v116, v153, v114
	s_waitcnt lgkmcnt(0)
	v_pk_add_f32 v[114:115], v[114:115], v[116:117]
	v_mov_b64_e32 v[116:117], s[0:1]
	s_mov_b32 s0, 0x3a800000
	v_pk_fma_f32 v[114:115], v[114:115], s[0:1], v[116:117] op_sel_hi:[1,0,0]
	s_nop 0
	v_mul_f32_e32 v105, 0x4b800000, v115
	v_cmp_gt_f32_e32 vcc, s25, v115
	s_nop 1
	v_cndmask_b32_e32 v105, v115, v105, vcc
	v_rsq_f32_e32 v105, v105
	s_nop 0
	v_mul_f32_e32 v115, 0x45800000, v105
	v_cndmask_b32_e32 v118, v105, v115, vcc
	v_pk_mul_f32 v[44:45], v[44:45], v[118:119] op_sel_hi:[1,0]
	v_pk_mul_f32 v[46:47], v[46:47], v[118:119] op_sel_hi:[1,0]
	v_pk_mul_f32 v[36:37], v[36:37], v[118:119] op_sel_hi:[1,0]
	s_waitcnt vmcnt(1)
	v_pk_fma_f32 v[44:45], v[92:93], v[44:45], v[76:77]
	v_pk_fma_f32 v[46:47], v[94:95], v[46:47], v[78:79]
	v_pk_mul_f32 v[40:41], v[40:41], v[118:119] op_sel_hi:[1,0]
	v_pk_mul_f32 v[42:43], v[42:43], v[118:119] op_sel_hi:[1,0]
	v_pk_fma_f32 v[36:37], v[68:69], v[36:37], v[72:73]
	v_pk_mul_f32 v[38:39], v[38:39], v[118:119] op_sel_hi:[1,0]
	v_cvt_pk_bf16_f32 v44, v44, v45
	v_cvt_pk_bf16_f32 v45, v46, v47
	v_pk_fma_f32 v[40:41], v[88:89], v[40:41], v[64:65]
	v_pk_fma_f32 v[42:43], v[90:91], v[42:43], v[66:67]
	v_pk_fma_f32 v[38:39], v[70:71], v[38:39], v[74:75]
	v_cvt_pk_bf16_f32 v36, v36, v37
	v_cvt_pk_bf16_f32 v40, v40, v41
	v_cvt_pk_bf16_f32 v41, v42, v43
	v_cvt_pk_bf16_f32 v37, v38, v39
	global_store_dwordx2 v[112:113], v[44:45], off
	global_store_dwordx2 v[112:113], v[40:41], off offset:512
	global_store_dwordx2 v[112:113], v[36:37], off offset:1024
	v_mul_f32_e32 v36, 0x4b800000, v114
	v_cmp_gt_f32_e32 vcc, s25, v114
	v_pk_mul_f32 v[32:33], v[32:33], v[118:119] op_sel_hi:[1,0]
	v_pk_mul_f32 v[34:35], v[34:35], v[118:119] op_sel_hi:[1,0]
	v_cndmask_b32_e32 v36, v114, v36, vcc
	v_rsq_f32_e32 v36, v36
	s_waitcnt vmcnt(3)
	v_pk_fma_f32 v[32:33], v[12:13], v[32:33], v[8:9]
	v_pk_fma_f32 v[34:35], v[14:15], v[34:35], v[10:11]
	v_cvt_pk_bf16_f32 v32, v32, v33
	v_cvt_pk_bf16_f32 v33, v34, v35
	global_store_dwordx2 v[112:113], v[32:33], off offset:1536
	v_mul_f32_e32 v32, 0x45800000, v36
	v_mov_b32_e32 v38, v85
	v_mov_b32_e32 v39, v81
	v_cndmask_b32_e32 v32, v36, v32, vcc
	v_mov_b32_e32 v36, v84
	v_mov_b32_e32 v37, v80
	v_pk_mul_f32 v[38:39], v[38:39], v[38:39]
	v_mov_b32_e32 v40, v49
	v_pk_fma_f32 v[36:37], v[36:37], v[36:37], v[38:39]
	v_mov_b32_e32 v38, v86
	v_mov_b32_e32 v39, v82
	v_pk_fma_f32 v[36:37], v[38:39], v[38:39], v[36:37]
	v_mov_b32_e32 v38, v87
	v_mov_b32_e32 v39, v83
	v_mov_b32_e32 v41, v53
	v_pk_fma_f32 v[36:37], v[38:39], v[38:39], v[36:37]
	v_mov_b32_e32 v38, v48
	v_mov_b32_e32 v39, v52
	v_pk_mul_f32 v[40:41], v[40:41], v[40:41]
	v_mov_b32_e32 v42, v61
	v_pk_fma_f32 v[38:39], v[38:39], v[38:39], v[40:41]
	v_mov_b32_e32 v40, v50
	v_mov_b32_e32 v41, v54
	v_pk_fma_f32 v[38:39], v[40:41], v[40:41], v[38:39]
	v_mov_b32_e32 v40, v51
	v_mov_b32_e32 v41, v55
	v_mov_b32_e32 v43, v57
	v_pk_fma_f32 v[38:39], v[40:41], v[40:41], v[38:39]
	v_mov_b32_e32 v40, v60
	v_mov_b32_e32 v41, v56
	v_pk_mul_f32 v[42:43], v[42:43], v[42:43]
	v_mov_b32_e32 v44, v1
	v_pk_fma_f32 v[40:41], v[40:41], v[40:41], v[42:43]
	v_mov_b32_e32 v42, v62
	v_mov_b32_e32 v43, v58
	v_pk_fma_f32 v[40:41], v[42:43], v[42:43], v[40:41]
	v_mov_b32_e32 v42, v63
	v_mov_b32_e32 v43, v59
	v_mov_b32_e32 v45, v5
	v_pk_fma_f32 v[40:41], v[42:43], v[42:43], v[40:41]
	v_mov_b32_e32 v42, v0
	v_mov_b32_e32 v43, v4
	v_pk_mul_f32 v[44:45], v[44:45], v[44:45]
	v_pk_mul_f32 v[28:29], v[28:29], v[32:33] op_sel_hi:[1,0]
	v_pk_fma_f32 v[42:43], v[42:43], v[42:43], v[44:45]
	v_mov_b32_e32 v44, v2
	v_mov_b32_e32 v45, v6
	v_pk_fma_f32 v[42:43], v[44:45], v[44:45], v[42:43]
	v_mov_b32_e32 v44, v3
	v_mov_b32_e32 v45, v7
	v_pk_fma_f32 v[42:43], v[44:45], v[44:45], v[42:43]
	v_mov_b32_e32 v44, v40
	v_mov_b32_e32 v45, v36
	v_mov_b32_e32 v36, v41
	v_pk_add_f32 v[36:37], v[44:45], v[36:37]
	v_mov_b32_e32 v40, v43
	v_mov_b32_e32 v41, v39
	v_pk_add_f32 v[36:37], v[40:41], v[36:37]
	v_mov_b32_e32 v43, v38
	v_pk_add_f32 v[36:37], v[42:43], v[36:37]
	ds_bpermute_b32 v39, v148, v37
	ds_bpermute_b32 v38, v148, v36
	v_pk_mul_f32 v[30:31], v[30:31], v[32:33] op_sel_hi:[1,0]
	v_pk_fma_f32 v[28:29], v[92:93], v[28:29], v[76:77]
	v_pk_fma_f32 v[30:31], v[94:95], v[30:31], v[78:79]
	v_cvt_pk_bf16_f32 v28, v28, v29
	v_cvt_pk_bf16_f32 v29, v30, v31
	s_waitcnt lgkmcnt(0)
	v_pk_add_f32 v[30:31], v[36:37], v[38:39]
	ds_bpermute_b32 v37, v149, v31
	ds_bpermute_b32 v36, v149, v30
	v_lshl_add_u64 v[34:35], v[100:101], 0, v[110:111]
	global_store_dwordx2 v[34:35], v[28:29], off
	v_pk_mul_f32 v[24:25], v[24:25], v[32:33] op_sel_hi:[1,0]
	v_pk_mul_f32 v[26:27], v[26:27], v[32:33] op_sel_hi:[1,0]
	s_waitcnt lgkmcnt(0)
	v_pk_add_f32 v[28:29], v[30:31], v[36:37]
	ds_bpermute_b32 v31, v150, v29
	ds_bpermute_b32 v30, v150, v28
	v_pk_fma_f32 v[24:25], v[88:89], v[24:25], v[64:65]
	v_pk_fma_f32 v[26:27], v[90:91], v[26:27], v[66:67]
	v_cvt_pk_bf16_f32 v24, v24, v25
	v_cvt_pk_bf16_f32 v25, v26, v27
	global_store_dwordx2 v[34:35], v[24:25], off offset:512
	s_waitcnt lgkmcnt(0)
	v_pk_add_f32 v[24:25], v[28:29], v[30:31]
	ds_bpermute_b32 v27, v151, v25
	ds_bpermute_b32 v26, v151, v24
	v_pk_mul_f32 v[20:21], v[20:21], v[32:33] op_sel_hi:[1,0]
	v_pk_mul_f32 v[22:23], v[22:23], v[32:33] op_sel_hi:[1,0]
	v_pk_fma_f32 v[20:21], v[68:69], v[20:21], v[72:73]
	v_pk_fma_f32 v[22:23], v[70:71], v[22:23], v[74:75]
	s_waitcnt lgkmcnt(0)
	v_pk_add_f32 v[24:25], v[24:25], v[26:27]
	ds_bpermute_b32 v27, v152, v25
	ds_bpermute_b32 v26, v152, v24
	v_cvt_pk_bf16_f32 v20, v20, v21
	v_cvt_pk_bf16_f32 v21, v22, v23
	global_store_dwordx2 v[34:35], v[20:21], off offset:1024
	v_pk_mul_f32 v[16:17], v[16:17], v[32:33] op_sel_hi:[1,0]
	s_waitcnt lgkmcnt(0)
	v_pk_add_f32 v[20:21], v[24:25], v[26:27]
	ds_bpermute_b32 v23, v153, v21
	ds_bpermute_b32 v22, v153, v20
	v_pk_fma_f32 v[16:17], v[12:13], v[16:17], v[8:9]
	v_pk_mul_f32 v[18:19], v[18:19], v[32:33] op_sel_hi:[1,0]
	v_cvt_pk_bf16_f32 v16, v16, v17
	v_pk_fma_f32 v[18:19], v[14:15], v[18:19], v[10:11]
	s_waitcnt lgkmcnt(0)
	v_pk_add_f32 v[20:21], v[20:21], v[22:23]
	s_nop 0
	v_pk_fma_f32 v[20:21], v[20:21], s[0:1], v[116:117] op_sel_hi:[1,0,0]
	s_nop 0
	v_mul_f32_e32 v17, 0x4b800000, v21
	v_cmp_gt_f32_e32 vcc, s25, v21
	s_nop 1
	v_cndmask_b32_e32 v17, v21, v17, vcc
	v_rsq_f32_e32 v21, v17
	v_cvt_pk_bf16_f32 v17, v18, v19
	global_store_dwordx2 v[34:35], v[16:17], off offset:1536
	v_lshl_add_u64 v[16:17], v[100:101], 0, v[108:109]
	v_mul_f32_e32 v18, 0x45800000, v21
	v_cndmask_b32_e32 v18, v21, v18, vcc
	v_pk_mul_f32 v[22:23], v[84:85], v[18:19] op_sel_hi:[1,0]
	v_pk_mul_f32 v[24:25], v[86:87], v[18:19] op_sel_hi:[1,0]
	v_pk_fma_f32 v[22:23], v[92:93], v[22:23], v[76:77]
	v_pk_fma_f32 v[24:25], v[94:95], v[24:25], v[78:79]
	v_cvt_pk_bf16_f32 v22, v22, v23
	v_cvt_pk_bf16_f32 v23, v24, v25
	global_store_dwordx2 v[16:17], v[22:23], off
	v_pk_mul_f32 v[22:23], v[80:81], v[18:19] op_sel_hi:[1,0]
	v_pk_mul_f32 v[24:25], v[82:83], v[18:19] op_sel_hi:[1,0]
	v_pk_fma_f32 v[22:23], v[88:89], v[22:23], v[64:65]
	v_pk_fma_f32 v[24:25], v[90:91], v[24:25], v[66:67]
	v_cvt_pk_bf16_f32 v22, v22, v23
	v_cvt_pk_bf16_f32 v23, v24, v25
	global_store_dwordx2 v[16:17], v[22:23], off offset:512
	v_pk_mul_f32 v[22:23], v[52:53], v[18:19] op_sel_hi:[1,0]
	v_pk_mul_f32 v[24:25], v[54:55], v[18:19] op_sel_hi:[1,0]
	v_mul_f32_e32 v21, 0x4b800000, v20
	v_cmp_gt_f32_e32 vcc, s25, v20
	v_pk_fma_f32 v[22:23], v[68:69], v[22:23], v[72:73]
	v_pk_fma_f32 v[24:25], v[70:71], v[24:25], v[74:75]
	v_cndmask_b32_e32 v20, v20, v21, vcc
	v_cvt_pk_bf16_f32 v22, v22, v23
	v_cvt_pk_bf16_f32 v23, v24, v25
	v_rsq_f32_e32 v24, v20
	global_store_dwordx2 v[16:17], v[22:23], off offset:1024
	v_pk_mul_f32 v[22:23], v[48:49], v[18:19] op_sel_hi:[1,0]
	v_pk_mul_f32 v[18:19], v[50:51], v[18:19] op_sel_hi:[1,0]
	v_pk_fma_f32 v[22:23], v[12:13], v[22:23], v[8:9]
	v_pk_fma_f32 v[18:19], v[14:15], v[18:19], v[10:11]
	v_cvt_pk_bf16_f32 v20, v22, v23
	v_cvt_pk_bf16_f32 v21, v18, v19
	global_store_dwordx2 v[16:17], v[20:21], off offset:1536
	v_mul_f32_e32 v16, 0x45800000, v24
	v_cndmask_b32_e32 v16, v24, v16, vcc
	v_pk_mul_f32 v[20:21], v[60:61], v[16:17] op_sel_hi:[1,0]
	v_pk_mul_f32 v[22:23], v[62:63], v[16:17] op_sel_hi:[1,0]
	v_pk_fma_f32 v[20:21], v[92:93], v[20:21], v[76:77]
	v_pk_fma_f32 v[22:23], v[94:95], v[22:23], v[78:79]
	v_lshl_add_u64 v[18:19], v[100:101], 0, v[106:107]
	v_cvt_pk_bf16_f32 v20, v20, v21
	v_cvt_pk_bf16_f32 v21, v22, v23
	global_store_dwordx2 v[18:19], v[20:21], off
	v_pk_mul_f32 v[20:21], v[56:57], v[16:17] op_sel_hi:[1,0]
	v_pk_mul_f32 v[22:23], v[58:59], v[16:17] op_sel_hi:[1,0]
	v_pk_mul_f32 v[4:5], v[4:5], v[16:17] op_sel_hi:[1,0]
	v_pk_mul_f32 v[6:7], v[6:7], v[16:17] op_sel_hi:[1,0]
	v_pk_mul_f32 v[0:1], v[0:1], v[16:17] op_sel_hi:[1,0]
	v_pk_mul_f32 v[2:3], v[2:3], v[16:17] op_sel_hi:[1,0]
	v_pk_fma_f32 v[20:21], v[88:89], v[20:21], v[64:65]
	v_pk_fma_f32 v[22:23], v[90:91], v[22:23], v[66:67]
	v_pk_fma_f32 v[4:5], v[68:69], v[4:5], v[72:73]
	v_pk_fma_f32 v[6:7], v[70:71], v[6:7], v[74:75]
	v_pk_fma_f32 v[0:1], v[12:13], v[0:1], v[8:9]
	v_pk_fma_f32 v[2:3], v[14:15], v[2:3], v[10:11]
	v_cvt_pk_bf16_f32 v20, v20, v21
	v_cvt_pk_bf16_f32 v21, v22, v23
	v_cvt_pk_bf16_f32 v4, v4, v5
	v_cvt_pk_bf16_f32 v5, v6, v7
	v_cvt_pk_bf16_f32 v0, v0, v1
	v_cvt_pk_bf16_f32 v1, v2, v3
	global_store_dwordx2 v[18:19], v[20:21], off offset:512
	global_store_dwordx2 v[18:19], v[4:5], off offset:1024
	global_store_dwordx2 v[18:19], v[0:1], off offset:1536
	s_branch .LBB0_1056
